# v25 with the query-pair lane layout for the merged sample-step dilated attention (half the VALU work, 5 key blocks in flight)
# speedup vs baseline: 1.0217x; 1.0145x over previous
.LBB0_419:
	s_and_b64 vcc, exec, s[0:1]
	s_cbranch_vccz .LBB0_1020
	s_add_i32 s0, s56, 0xf800
	s_and_b32 s1, s0, 0xffff
	s_mul_i32 s1, s1, 0xcccd
	s_lshr_b32 s44, s1, 19
	s_mul_i32 s1, s44, 10
	s_sub_i32 s0, s0, s1
	s_and_b32 s57, s0, 0xffff
	s_cmp_gt_u32 s57, 1
	s_mov_b64 s[0:1], -1
	s_cbranch_scc0 .LBB0_920
	s_cmp_lt_u32 s57, 6
	s_cbranch_scc0 .LBB0_768
	s_cmp_ge_u32 s57, 4
	s_cbranch_scc1 .Lst5_done
	v_readfirstlane_b32 s4, v192
	s_sub_u32 s0, s57, 1
	s_lshl_b32 s0, s0, 1
	s_lshr_b32 s4, s4, 6
	s_movk_i32 s1, 0x80
	s_lshl_b32 s1, s1, s0
	s_cmp_eq_u32 s0, 2
	s_cselect_b32 s6, s82, s84
	s_cselect_b32 s7, s83, s85
	s_mov_b32 s29, 0x9a40000
	s_cselect_b32 s29, 0x5a40000, s29
	s_add_u32 s30, s0, 17
	s_lshl_b32 s31, s44, s30
	s_add_u32 s6, s6, s31
	s_addc_u32 s7, s7, 0
	s_add_u32 s10, s36, s29
	s_addc_u32 s11, s37, 0
	s_add_u32 s10, s10, s31
	s_addc_u32 s11, s11, 0
	s_sub_u32 s10, s10, 0x2000
	s_subb_u32 s11, s11, 0
	s_lshl_b32 s18, 0x400, s0
	s_lshl_b32 s64, s18, 3
	s_lshl_b32 s28, s44, 3
	s_mul_i32 s30, s28, 0x600
	s_lshl_b32 s31, s0, 8
	s_add_u32 s30, s30, s31
	s_add_u32 s12, s38, 0x784da00
	s_addc_u32 s13, s39, 0
	s_add_u32 s12, s12, s30
	s_addc_u32 s13, s13, 0
	s_add_u32 s29, s28, 0x4000
	s_add_u32 s29, s29, s4
	s_mul_i32 s30, s29, 0x300
	s_lshl_b32 s31, s0, 7
	s_add_u32 s30, s30, s31
	s_add_u32 s14, s38, 0x988da00
	s_addc_u32 s15, s39, 0
	s_add_u32 s14, s14, s30
	s_addc_u32 s15, s15, 0
	s_mul_i32 s30, s29, 24
	s_lshl_b32 s31, s0, 2
	s_add_u32 s30, s30, s31
	s_add_u32 s22, s38, 0xa54da00
	s_addc_u32 s23, s39, 0
	s_add_u32 s22, s22, s30
	s_addc_u32 s23, s23, 0
	v_and_b32_e32 v218, 63, v192
	v_and_b32_e32 v219, 31, v218
	v_lshrrev_b32_e32 v220, 5, v218
	v_lshlrev_b32_e32 v219, 4, v219
	v_lshl_add_u32 v214, v220, 10, v219
	v_mul_u32_u24_e32 v216, 0x600, v220
	v_add_u32_e32 v216, v216, v219
	global_load_dwordx4 v[164:167], v216, s[12:13]
	s_add_u32 s12, s12, 0xc00
	s_addc_u32 s13, s13, 0
	global_load_dwordx4 v[168:171], v216, s[12:13]
	s_add_u32 s12, s12, 0xc00
	s_addc_u32 s13, s13, 0
	global_load_dwordx4 v[172:175], v216, s[12:13]
	s_add_u32 s12, s12, 0xc00
	s_addc_u32 s13, s13, 0
	global_load_dwordx4 v[176:179], v216, s[12:13]
	s_mul_i32 s28, s4, s18
	s_lshl_b32 s30, s1, 10
	s_sub_u32 s28, s30, s28
	s_add_u32 s31, s28, 0x0
	s_cmp_ge_u32 s31, s30
	s_cselect_b32 s42, s10, s6
	s_cselect_b32 s43, s11, s7
	s_add_u32 s42, s42, s31
	s_addc_u32 s43, s43, 0
	global_load_dwordx4 v[0:3], v214, s[42:43] nt
	global_load_dwordx4 v[16:19], v214, s[42:43] offset:512 nt
	s_add_u32 s31, s28, 0x800
	s_cmp_ge_u32 s31, s30
	s_cselect_b32 s42, s10, s6
	s_cselect_b32 s43, s11, s7
	s_add_u32 s42, s42, s31
	s_addc_u32 s43, s43, 0
	global_load_dwordx4 v[4:7], v214, s[42:43] nt
	global_load_dwordx4 v[20:23], v214, s[42:43] offset:512 nt
	s_add_u32 s31, s28, 0x1000
	s_cmp_ge_u32 s31, s30
	s_cselect_b32 s42, s10, s6
	s_cselect_b32 s43, s11, s7
	s_add_u32 s42, s42, s31
	s_addc_u32 s43, s43, 0
	global_load_dwordx4 v[8:11], v214, s[42:43] nt
	global_load_dwordx4 v[24:27], v214, s[42:43] offset:512 nt
	s_add_u32 s31, s28, 0x1800
	s_cmp_ge_u32 s31, s30
	s_cselect_b32 s42, s10, s6
	s_cselect_b32 s43, s11, s7
	s_add_u32 s42, s42, s31
	s_addc_u32 s43, s43, 0
	global_load_dwordx4 v[12:15], v214, s[42:43] nt
	global_load_dwordx4 v[28:31], v214, s[42:43] offset:512 nt
	s_add_u32 s62, s6, s28
	s_addc_u32 s63, s7, 0
	s_sub_u32 s62, s62, s64
	s_subb_u32 s63, s63, 0
	s_add_u32 s42, s62, 0x1000
	s_addc_u32 s43, s63, 0
	global_load_dwordx4 v[32:35], v214, s[62:63] nt
	global_load_dwordx4 v[48:51], v214, s[62:63] offset:512 nt
	global_load_dwordx4 v[36:39], v214, s[62:63] offset:2048 nt
	global_load_dwordx4 v[52:55], v214, s[62:63] offset:2560 nt
	global_load_dwordx4 v[40:43], v214, s[42:43] nt
	global_load_dwordx4 v[56:59], v214, s[42:43] offset:512 nt
	global_load_dwordx4 v[44:47], v214, s[42:43] offset:2048 nt
	global_load_dwordx4 v[60:63], v214, s[42:43] offset:2560 nt
	s_sub_u32 s62, s62, s64
	s_subb_u32 s63, s63, 0
	s_add_u32 s42, s62, 0x1000
	s_addc_u32 s43, s63, 0
	global_load_dwordx4 v[64:67], v214, s[62:63] nt
	global_load_dwordx4 v[80:83], v214, s[62:63] offset:512 nt
	global_load_dwordx4 v[68:71], v214, s[62:63] offset:2048 nt
	global_load_dwordx4 v[84:87], v214, s[62:63] offset:2560 nt
	global_load_dwordx4 v[72:75], v214, s[42:43] nt
	global_load_dwordx4 v[88:91], v214, s[42:43] offset:512 nt
	global_load_dwordx4 v[76:79], v214, s[42:43] offset:2048 nt
	global_load_dwordx4 v[92:95], v214, s[42:43] offset:2560 nt
	s_sub_u32 s62, s62, s64
	s_subb_u32 s63, s63, 0
	s_add_u32 s42, s62, 0x1000
	s_addc_u32 s43, s63, 0
	global_load_dwordx4 v[96:99], v214, s[62:63] nt
	global_load_dwordx4 v[112:115], v214, s[62:63] offset:512 nt
	global_load_dwordx4 v[100:103], v214, s[62:63] offset:2048 nt
	global_load_dwordx4 v[116:119], v214, s[62:63] offset:2560 nt
	global_load_dwordx4 v[104:107], v214, s[42:43] nt
	global_load_dwordx4 v[120:123], v214, s[42:43] offset:512 nt
	global_load_dwordx4 v[108:111], v214, s[42:43] offset:2048 nt
	global_load_dwordx4 v[124:127], v214, s[42:43] offset:2560 nt
	s_sub_u32 s62, s62, s64
	s_subb_u32 s63, s63, 0
	s_add_u32 s42, s62, 0x1000
	s_addc_u32 s43, s63, 0
	global_load_dwordx4 v[128:131], v214, s[62:63] nt
	global_load_dwordx4 v[146:149], v214, s[62:63] offset:512 nt
	global_load_dwordx4 v[132:135], v214, s[62:63] offset:2048 nt
	global_load_dwordx4 v[150:153], v214, s[62:63] offset:2560 nt
	global_load_dwordx4 v[138:141], v214, s[42:43] nt
	global_load_dwordx4 v[154:157], v214, s[42:43] offset:512 nt
	global_load_dwordx4 v[142:145], v214, s[42:43] offset:2048 nt
	global_load_dwordx4 v[158:161], v214, s[42:43] offset:2560 nt
	v_mov_b32_e32 v200, 0xff7fffff
	v_mov_b32_e32 v204, 0
	v_mov_b32_e32 v180, 0
	v_mov_b32_e32 v181, 0
	v_mov_b32_e32 v182, 0
	v_mov_b32_e32 v183, 0
	v_mov_b32_e32 v201, 0xff7fffff
	v_mov_b32_e32 v205, 0
	v_mov_b32_e32 v184, 0
	v_mov_b32_e32 v185, 0
	v_mov_b32_e32 v186, 0
	v_mov_b32_e32 v187, 0
	v_mov_b32_e32 v202, 0xff7fffff
	v_mov_b32_e32 v206, 0
	v_mov_b32_e32 v188, 0
	v_mov_b32_e32 v189, 0
	v_mov_b32_e32 v190, 0
	v_mov_b32_e32 v191, 0
	v_mov_b32_e32 v203, 0xff7fffff
	v_mov_b32_e32 v207, 0
	v_mov_b32_e32 v196, 0
	v_mov_b32_e32 v197, 0
	v_mov_b32_e32 v198, 0
	v_mov_b32_e32 v199, 0
	s_waitcnt vmcnt(39)
	v_mul_f32_e32 v208, v164, v0
	v_fmac_f32_e32 v208, v165, v1
	v_fmac_f32_e32 v208, v166, v2
	v_fmac_f32_e32 v208, v167, v3
	s_waitcnt vmcnt(37)
	v_mul_f32_e32 v209, v168, v4
	v_fmac_f32_e32 v209, v169, v5
	v_fmac_f32_e32 v209, v170, v6
	v_fmac_f32_e32 v209, v171, v7
	s_waitcnt vmcnt(35)
	v_mul_f32_e32 v210, v172, v8
	v_fmac_f32_e32 v210, v173, v9
	v_fmac_f32_e32 v210, v174, v10
	v_fmac_f32_e32 v210, v175, v11
	s_waitcnt vmcnt(33)
	v_mul_f32_e32 v212, v176, v12
	v_fmac_f32_e32 v212, v177, v13
	v_fmac_f32_e32 v212, v178, v14
	v_fmac_f32_e32 v212, v179, v15
	v_add_f32_dpp v208, v208, v208 quad_perm:[1,0,3,2] row_mask:0xf bank_mask:0xf bound_ctrl:1
	v_add_f32_dpp v209, v209, v209 quad_perm:[1,0,3,2] row_mask:0xf bank_mask:0xf bound_ctrl:1
	v_add_f32_dpp v210, v210, v210 quad_perm:[1,0,3,2] row_mask:0xf bank_mask:0xf bound_ctrl:1
	v_add_f32_dpp v212, v212, v212 quad_perm:[1,0,3,2] row_mask:0xf bank_mask:0xf bound_ctrl:1
	v_add_f32_dpp v208, v208, v208 quad_perm:[2,3,0,1] row_mask:0xf bank_mask:0xf bound_ctrl:1
	v_add_f32_dpp v209, v209, v209 quad_perm:[2,3,0,1] row_mask:0xf bank_mask:0xf bound_ctrl:1
	v_add_f32_dpp v210, v210, v210 quad_perm:[2,3,0,1] row_mask:0xf bank_mask:0xf bound_ctrl:1
	v_add_f32_dpp v212, v212, v212 quad_perm:[2,3,0,1] row_mask:0xf bank_mask:0xf bound_ctrl:1
	v_add_f32_dpp v208, v208, v208 row_ror:4 row_mask:0xf bank_mask:0xf bound_ctrl:1
	v_add_f32_dpp v209, v209, v209 row_ror:4 row_mask:0xf bank_mask:0xf bound_ctrl:1
	v_add_f32_dpp v210, v210, v210 row_ror:4 row_mask:0xf bank_mask:0xf bound_ctrl:1
	v_add_f32_dpp v212, v212, v212 row_ror:4 row_mask:0xf bank_mask:0xf bound_ctrl:1
	v_add_f32_dpp v208, v208, v208 row_ror:8 row_mask:0xf bank_mask:0xf bound_ctrl:1
	v_add_f32_dpp v209, v209, v209 row_ror:8 row_mask:0xf bank_mask:0xf bound_ctrl:1
	v_add_f32_dpp v210, v210, v210 row_ror:8 row_mask:0xf bank_mask:0xf bound_ctrl:1
	v_add_f32_dpp v212, v212, v212 row_ror:8 row_mask:0xf bank_mask:0xf bound_ctrl:1
	v_max_f32_e32 v218, v208, v200
	v_sub_f32_e32 v217, v200, v218
	v_sub_f32_e32 v208, v208, v218
	v_mul_f32_e32 v217, 0x3fb8aa3b, v217
	v_mul_f32_e32 v208, 0x3fb8aa3b, v208
	v_exp_f32_e32 v217, v217
	v_exp_f32_e32 v208, v208
	v_mov_b32_e32 v200, v218
	s_waitcnt vmcnt(38)
	v_fma_f32 v204, v204, v217, v208
	v_mul_f32_e32 v180, v180, v217
	v_mul_f32_e32 v181, v181, v217
	v_mul_f32_e32 v182, v182, v217
	v_mul_f32_e32 v183, v183, v217
	v_fmac_f32_e32 v180, v208, v16
	v_fmac_f32_e32 v181, v208, v17
	v_fmac_f32_e32 v182, v208, v18
	v_fmac_f32_e32 v183, v208, v19
	v_max_f32_e32 v218, v209, v201
	v_sub_f32_e32 v217, v201, v218
	v_sub_f32_e32 v209, v209, v218
	v_mul_f32_e32 v217, 0x3fb8aa3b, v217
	v_mul_f32_e32 v209, 0x3fb8aa3b, v209
	v_exp_f32_e32 v217, v217
	v_exp_f32_e32 v209, v209
	v_mov_b32_e32 v201, v218
	s_waitcnt vmcnt(36)
	v_fma_f32 v205, v205, v217, v209
	v_mul_f32_e32 v184, v184, v217
	v_mul_f32_e32 v185, v185, v217
	v_mul_f32_e32 v186, v186, v217
	v_mul_f32_e32 v187, v187, v217
	v_fmac_f32_e32 v184, v209, v20
	v_fmac_f32_e32 v185, v209, v21
	v_fmac_f32_e32 v186, v209, v22
	v_fmac_f32_e32 v187, v209, v23
	v_max_f32_e32 v218, v210, v202
	v_sub_f32_e32 v217, v202, v218
	v_sub_f32_e32 v210, v210, v218
	v_mul_f32_e32 v217, 0x3fb8aa3b, v217
	v_mul_f32_e32 v210, 0x3fb8aa3b, v210
	v_exp_f32_e32 v217, v217
	v_exp_f32_e32 v210, v210
	v_mov_b32_e32 v202, v218
	s_waitcnt vmcnt(34)
	v_fma_f32 v206, v206, v217, v210
	v_mul_f32_e32 v188, v188, v217
	v_mul_f32_e32 v189, v189, v217
	v_mul_f32_e32 v190, v190, v217
	v_mul_f32_e32 v191, v191, v217
	v_fmac_f32_e32 v188, v210, v24
	v_fmac_f32_e32 v189, v210, v25
	v_fmac_f32_e32 v190, v210, v26
	v_fmac_f32_e32 v191, v210, v27
	v_max_f32_e32 v218, v212, v203
	v_sub_f32_e32 v217, v203, v218
	v_sub_f32_e32 v212, v212, v218
	v_mul_f32_e32 v217, 0x3fb8aa3b, v217
	v_mul_f32_e32 v212, 0x3fb8aa3b, v212
	v_exp_f32_e32 v217, v217
	v_exp_f32_e32 v212, v212
	v_mov_b32_e32 v203, v218
	s_waitcnt vmcnt(32)
	v_fma_f32 v207, v207, v217, v212
	v_mul_f32_e32 v196, v196, v217
	v_mul_f32_e32 v197, v197, v217
	v_mul_f32_e32 v198, v198, v217
	v_mul_f32_e32 v199, v199, v217
	v_fmac_f32_e32 v196, v212, v28
	v_fmac_f32_e32 v197, v212, v29
	v_fmac_f32_e32 v198, v212, v30
	v_fmac_f32_e32 v199, v212, v31
	s_sub_u32 s62, s62, s64
	s_subb_u32 s63, s63, 0
	s_add_u32 s42, s62, 0x1000
	s_addc_u32 s43, s63, 0
	global_load_dwordx4 v[0:3], v214, s[62:63] nt
	global_load_dwordx4 v[16:19], v214, s[62:63] offset:512 nt
	global_load_dwordx4 v[4:7], v214, s[62:63] offset:2048 nt
	global_load_dwordx4 v[20:23], v214, s[62:63] offset:2560 nt
	global_load_dwordx4 v[8:11], v214, s[42:43] nt
	global_load_dwordx4 v[24:27], v214, s[42:43] offset:512 nt
	global_load_dwordx4 v[12:15], v214, s[42:43] offset:2048 nt
	global_load_dwordx4 v[28:31], v214, s[42:43] offset:2560 nt
	s_waitcnt vmcnt(39)
	v_mul_f32_e32 v208, v164, v32
	v_fmac_f32_e32 v208, v165, v33
	v_fmac_f32_e32 v208, v166, v34
	v_fmac_f32_e32 v208, v167, v35
	s_waitcnt vmcnt(37)
	v_mul_f32_e32 v209, v168, v36
	v_fmac_f32_e32 v209, v169, v37
	v_fmac_f32_e32 v209, v170, v38
	v_fmac_f32_e32 v209, v171, v39
	s_waitcnt vmcnt(35)
	v_mul_f32_e32 v210, v172, v40
	v_fmac_f32_e32 v210, v173, v41
	v_fmac_f32_e32 v210, v174, v42
	v_fmac_f32_e32 v210, v175, v43
	s_waitcnt vmcnt(33)
	v_mul_f32_e32 v212, v176, v44
	v_fmac_f32_e32 v212, v177, v45
	v_fmac_f32_e32 v212, v178, v46
	v_fmac_f32_e32 v212, v179, v47
	v_add_f32_dpp v208, v208, v208 quad_perm:[1,0,3,2] row_mask:0xf bank_mask:0xf bound_ctrl:1
	v_add_f32_dpp v209, v209, v209 quad_perm:[1,0,3,2] row_mask:0xf bank_mask:0xf bound_ctrl:1
	v_add_f32_dpp v210, v210, v210 quad_perm:[1,0,3,2] row_mask:0xf bank_mask:0xf bound_ctrl:1
	v_add_f32_dpp v212, v212, v212 quad_perm:[1,0,3,2] row_mask:0xf bank_mask:0xf bound_ctrl:1
	v_add_f32_dpp v208, v208, v208 quad_perm:[2,3,0,1] row_mask:0xf bank_mask:0xf bound_ctrl:1
	v_add_f32_dpp v209, v209, v209 quad_perm:[2,3,0,1] row_mask:0xf bank_mask:0xf bound_ctrl:1
	v_add_f32_dpp v210, v210, v210 quad_perm:[2,3,0,1] row_mask:0xf bank_mask:0xf bound_ctrl:1
	v_add_f32_dpp v212, v212, v212 quad_perm:[2,3,0,1] row_mask:0xf bank_mask:0xf bound_ctrl:1
	v_add_f32_dpp v208, v208, v208 row_ror:4 row_mask:0xf bank_mask:0xf bound_ctrl:1
	v_add_f32_dpp v209, v209, v209 row_ror:4 row_mask:0xf bank_mask:0xf bound_ctrl:1
	v_add_f32_dpp v210, v210, v210 row_ror:4 row_mask:0xf bank_mask:0xf bound_ctrl:1
	v_add_f32_dpp v212, v212, v212 row_ror:4 row_mask:0xf bank_mask:0xf bound_ctrl:1
	v_add_f32_dpp v208, v208, v208 row_ror:8 row_mask:0xf bank_mask:0xf bound_ctrl:1
	v_add_f32_dpp v209, v209, v209 row_ror:8 row_mask:0xf bank_mask:0xf bound_ctrl:1
	v_add_f32_dpp v210, v210, v210 row_ror:8 row_mask:0xf bank_mask:0xf bound_ctrl:1
	v_add_f32_dpp v212, v212, v212 row_ror:8 row_mask:0xf bank_mask:0xf bound_ctrl:1
	v_max_f32_e32 v218, v208, v200
	v_sub_f32_e32 v217, v200, v218
	v_sub_f32_e32 v208, v208, v218
	v_mul_f32_e32 v217, 0x3fb8aa3b, v217
	v_mul_f32_e32 v208, 0x3fb8aa3b, v208
	v_exp_f32_e32 v217, v217
	v_exp_f32_e32 v208, v208
	v_mov_b32_e32 v200, v218
	s_waitcnt vmcnt(38)
	v_fma_f32 v204, v204, v217, v208
	v_mul_f32_e32 v180, v180, v217
	v_mul_f32_e32 v181, v181, v217
	v_mul_f32_e32 v182, v182, v217
	v_mul_f32_e32 v183, v183, v217
	v_fmac_f32_e32 v180, v208, v48
	v_fmac_f32_e32 v181, v208, v49
	v_fmac_f32_e32 v182, v208, v50
	v_fmac_f32_e32 v183, v208, v51
	v_max_f32_e32 v218, v209, v201
	v_sub_f32_e32 v217, v201, v218
	v_sub_f32_e32 v209, v209, v218
	v_mul_f32_e32 v217, 0x3fb8aa3b, v217
	v_mul_f32_e32 v209, 0x3fb8aa3b, v209
	v_exp_f32_e32 v217, v217
	v_exp_f32_e32 v209, v209
	v_mov_b32_e32 v201, v218
	s_waitcnt vmcnt(36)
	v_fma_f32 v205, v205, v217, v209
	v_mul_f32_e32 v184, v184, v217
	v_mul_f32_e32 v185, v185, v217
	v_mul_f32_e32 v186, v186, v217
	v_mul_f32_e32 v187, v187, v217
	v_fmac_f32_e32 v184, v209, v52
	v_fmac_f32_e32 v185, v209, v53
	v_fmac_f32_e32 v186, v209, v54
	v_fmac_f32_e32 v187, v209, v55
	v_max_f32_e32 v218, v210, v202
	v_sub_f32_e32 v217, v202, v218
	v_sub_f32_e32 v210, v210, v218
	v_mul_f32_e32 v217, 0x3fb8aa3b, v217
	v_mul_f32_e32 v210, 0x3fb8aa3b, v210
	v_exp_f32_e32 v217, v217
	v_exp_f32_e32 v210, v210
	v_mov_b32_e32 v202, v218
	s_waitcnt vmcnt(34)
	v_fma_f32 v206, v206, v217, v210
	v_mul_f32_e32 v188, v188, v217
	v_mul_f32_e32 v189, v189, v217
	v_mul_f32_e32 v190, v190, v217
	v_mul_f32_e32 v191, v191, v217
	v_fmac_f32_e32 v188, v210, v56
	v_fmac_f32_e32 v189, v210, v57
	v_fmac_f32_e32 v190, v210, v58
	v_fmac_f32_e32 v191, v210, v59
	v_max_f32_e32 v218, v212, v203
	v_sub_f32_e32 v217, v203, v218
	v_sub_f32_e32 v212, v212, v218
	v_mul_f32_e32 v217, 0x3fb8aa3b, v217
	v_mul_f32_e32 v212, 0x3fb8aa3b, v212
	v_exp_f32_e32 v217, v217
	v_exp_f32_e32 v212, v212
	v_mov_b32_e32 v203, v218
	s_waitcnt vmcnt(32)
	v_fma_f32 v207, v207, v217, v212
	v_mul_f32_e32 v196, v196, v217
	v_mul_f32_e32 v197, v197, v217
	v_mul_f32_e32 v198, v198, v217
	v_mul_f32_e32 v199, v199, v217
	v_fmac_f32_e32 v196, v212, v60
	v_fmac_f32_e32 v197, v212, v61
	v_fmac_f32_e32 v198, v212, v62
	v_fmac_f32_e32 v199, v212, v63
	s_sub_u32 s62, s62, s64
	s_subb_u32 s63, s63, 0
	s_add_u32 s42, s62, 0x1000
	s_addc_u32 s43, s63, 0
	global_load_dwordx4 v[32:35], v214, s[62:63] nt
	global_load_dwordx4 v[48:51], v214, s[62:63] offset:512 nt
	global_load_dwordx4 v[36:39], v214, s[62:63] offset:2048 nt
	global_load_dwordx4 v[52:55], v214, s[62:63] offset:2560 nt
	global_load_dwordx4 v[40:43], v214, s[42:43] nt
	global_load_dwordx4 v[56:59], v214, s[42:43] offset:512 nt
	global_load_dwordx4 v[44:47], v214, s[42:43] offset:2048 nt
	global_load_dwordx4 v[60:63], v214, s[42:43] offset:2560 nt
	s_waitcnt vmcnt(39)
	v_mul_f32_e32 v208, v164, v64
	v_fmac_f32_e32 v208, v165, v65
	v_fmac_f32_e32 v208, v166, v66
	v_fmac_f32_e32 v208, v167, v67
	s_waitcnt vmcnt(37)
	v_mul_f32_e32 v209, v168, v68
	v_fmac_f32_e32 v209, v169, v69
	v_fmac_f32_e32 v209, v170, v70
	v_fmac_f32_e32 v209, v171, v71
	s_waitcnt vmcnt(35)
	v_mul_f32_e32 v210, v172, v72
	v_fmac_f32_e32 v210, v173, v73
	v_fmac_f32_e32 v210, v174, v74
	v_fmac_f32_e32 v210, v175, v75
	s_waitcnt vmcnt(33)
	v_mul_f32_e32 v212, v176, v76
	v_fmac_f32_e32 v212, v177, v77
	v_fmac_f32_e32 v212, v178, v78
	v_fmac_f32_e32 v212, v179, v79
	v_add_f32_dpp v208, v208, v208 quad_perm:[1,0,3,2] row_mask:0xf bank_mask:0xf bound_ctrl:1
	v_add_f32_dpp v209, v209, v209 quad_perm:[1,0,3,2] row_mask:0xf bank_mask:0xf bound_ctrl:1
	v_add_f32_dpp v210, v210, v210 quad_perm:[1,0,3,2] row_mask:0xf bank_mask:0xf bound_ctrl:1
	v_add_f32_dpp v212, v212, v212 quad_perm:[1,0,3,2] row_mask:0xf bank_mask:0xf bound_ctrl:1
	v_add_f32_dpp v208, v208, v208 quad_perm:[2,3,0,1] row_mask:0xf bank_mask:0xf bound_ctrl:1
	v_add_f32_dpp v209, v209, v209 quad_perm:[2,3,0,1] row_mask:0xf bank_mask:0xf bound_ctrl:1
	v_add_f32_dpp v210, v210, v210 quad_perm:[2,3,0,1] row_mask:0xf bank_mask:0xf bound_ctrl:1
	v_add_f32_dpp v212, v212, v212 quad_perm:[2,3,0,1] row_mask:0xf bank_mask:0xf bound_ctrl:1
	v_add_f32_dpp v208, v208, v208 row_ror:4 row_mask:0xf bank_mask:0xf bound_ctrl:1
	v_add_f32_dpp v209, v209, v209 row_ror:4 row_mask:0xf bank_mask:0xf bound_ctrl:1
	v_add_f32_dpp v210, v210, v210 row_ror:4 row_mask:0xf bank_mask:0xf bound_ctrl:1
	v_add_f32_dpp v212, v212, v212 row_ror:4 row_mask:0xf bank_mask:0xf bound_ctrl:1
	v_add_f32_dpp v208, v208, v208 row_ror:8 row_mask:0xf bank_mask:0xf bound_ctrl:1
	v_add_f32_dpp v209, v209, v209 row_ror:8 row_mask:0xf bank_mask:0xf bound_ctrl:1
	v_add_f32_dpp v210, v210, v210 row_ror:8 row_mask:0xf bank_mask:0xf bound_ctrl:1
	v_add_f32_dpp v212, v212, v212 row_ror:8 row_mask:0xf bank_mask:0xf bound_ctrl:1
	v_max_f32_e32 v218, v208, v200
	v_sub_f32_e32 v217, v200, v218
	v_sub_f32_e32 v208, v208, v218
	v_mul_f32_e32 v217, 0x3fb8aa3b, v217
	v_mul_f32_e32 v208, 0x3fb8aa3b, v208
	v_exp_f32_e32 v217, v217
	v_exp_f32_e32 v208, v208
	v_mov_b32_e32 v200, v218
	s_waitcnt vmcnt(38)
	v_fma_f32 v204, v204, v217, v208
	v_mul_f32_e32 v180, v180, v217
	v_mul_f32_e32 v181, v181, v217
	v_mul_f32_e32 v182, v182, v217
	v_mul_f32_e32 v183, v183, v217
	v_fmac_f32_e32 v180, v208, v80
	v_fmac_f32_e32 v181, v208, v81
	v_fmac_f32_e32 v182, v208, v82
	v_fmac_f32_e32 v183, v208, v83
	v_max_f32_e32 v218, v209, v201
	v_sub_f32_e32 v217, v201, v218
	v_sub_f32_e32 v209, v209, v218
	v_mul_f32_e32 v217, 0x3fb8aa3b, v217
	v_mul_f32_e32 v209, 0x3fb8aa3b, v209
	v_exp_f32_e32 v217, v217
	v_exp_f32_e32 v209, v209
	v_mov_b32_e32 v201, v218
	s_waitcnt vmcnt(36)
	v_fma_f32 v205, v205, v217, v209
	v_mul_f32_e32 v184, v184, v217
	v_mul_f32_e32 v185, v185, v217
	v_mul_f32_e32 v186, v186, v217
	v_mul_f32_e32 v187, v187, v217
	v_fmac_f32_e32 v184, v209, v84
	v_fmac_f32_e32 v185, v209, v85
	v_fmac_f32_e32 v186, v209, v86
	v_fmac_f32_e32 v187, v209, v87
	v_max_f32_e32 v218, v210, v202
	v_sub_f32_e32 v217, v202, v218
	v_sub_f32_e32 v210, v210, v218
	v_mul_f32_e32 v217, 0x3fb8aa3b, v217
	v_mul_f32_e32 v210, 0x3fb8aa3b, v210
	v_exp_f32_e32 v217, v217
	v_exp_f32_e32 v210, v210
	v_mov_b32_e32 v202, v218
	s_waitcnt vmcnt(34)
	v_fma_f32 v206, v206, v217, v210
	v_mul_f32_e32 v188, v188, v217
	v_mul_f32_e32 v189, v189, v217
	v_mul_f32_e32 v190, v190, v217
	v_mul_f32_e32 v191, v191, v217
	v_fmac_f32_e32 v188, v210, v88
	v_fmac_f32_e32 v189, v210, v89
	v_fmac_f32_e32 v190, v210, v90
	v_fmac_f32_e32 v191, v210, v91
	v_max_f32_e32 v218, v212, v203
	v_sub_f32_e32 v217, v203, v218
	v_sub_f32_e32 v212, v212, v218
	v_mul_f32_e32 v217, 0x3fb8aa3b, v217
	v_mul_f32_e32 v212, 0x3fb8aa3b, v212
	v_exp_f32_e32 v217, v217
	v_exp_f32_e32 v212, v212
	v_mov_b32_e32 v203, v218
	s_waitcnt vmcnt(32)
	v_fma_f32 v207, v207, v217, v212
	v_mul_f32_e32 v196, v196, v217
	v_mul_f32_e32 v197, v197, v217
	v_mul_f32_e32 v198, v198, v217
	v_mul_f32_e32 v199, v199, v217
	v_fmac_f32_e32 v196, v212, v92
	v_fmac_f32_e32 v197, v212, v93
	v_fmac_f32_e32 v198, v212, v94
	v_fmac_f32_e32 v199, v212, v95
	s_sub_u32 s62, s62, s64
	s_subb_u32 s63, s63, 0
	s_add_u32 s42, s62, 0x1000
	s_addc_u32 s43, s63, 0
	global_load_dwordx4 v[64:67], v214, s[62:63] nt
	global_load_dwordx4 v[80:83], v214, s[62:63] offset:512 nt
	global_load_dwordx4 v[68:71], v214, s[62:63] offset:2048 nt
	global_load_dwordx4 v[84:87], v214, s[62:63] offset:2560 nt
	global_load_dwordx4 v[72:75], v214, s[42:43] nt
	global_load_dwordx4 v[88:91], v214, s[42:43] offset:512 nt
	global_load_dwordx4 v[76:79], v214, s[42:43] offset:2048 nt
	global_load_dwordx4 v[92:95], v214, s[42:43] offset:2560 nt
	s_waitcnt vmcnt(39)
	v_mul_f32_e32 v208, v164, v96
	v_fmac_f32_e32 v208, v165, v97
	v_fmac_f32_e32 v208, v166, v98
	v_fmac_f32_e32 v208, v167, v99
	s_waitcnt vmcnt(37)
	v_mul_f32_e32 v209, v168, v100
	v_fmac_f32_e32 v209, v169, v101
	v_fmac_f32_e32 v209, v170, v102
	v_fmac_f32_e32 v209, v171, v103
	s_waitcnt vmcnt(35)
	v_mul_f32_e32 v210, v172, v104
	v_fmac_f32_e32 v210, v173, v105
	v_fmac_f32_e32 v210, v174, v106
	v_fmac_f32_e32 v210, v175, v107
	s_waitcnt vmcnt(33)
	v_mul_f32_e32 v212, v176, v108
	v_fmac_f32_e32 v212, v177, v109
	v_fmac_f32_e32 v212, v178, v110
	v_fmac_f32_e32 v212, v179, v111
	v_add_f32_dpp v208, v208, v208 quad_perm:[1,0,3,2] row_mask:0xf bank_mask:0xf bound_ctrl:1
	v_add_f32_dpp v209, v209, v209 quad_perm:[1,0,3,2] row_mask:0xf bank_mask:0xf bound_ctrl:1
	v_add_f32_dpp v210, v210, v210 quad_perm:[1,0,3,2] row_mask:0xf bank_mask:0xf bound_ctrl:1
	v_add_f32_dpp v212, v212, v212 quad_perm:[1,0,3,2] row_mask:0xf bank_mask:0xf bound_ctrl:1
	v_add_f32_dpp v208, v208, v208 quad_perm:[2,3,0,1] row_mask:0xf bank_mask:0xf bound_ctrl:1
	v_add_f32_dpp v209, v209, v209 quad_perm:[2,3,0,1] row_mask:0xf bank_mask:0xf bound_ctrl:1
	v_add_f32_dpp v210, v210, v210 quad_perm:[2,3,0,1] row_mask:0xf bank_mask:0xf bound_ctrl:1
	v_add_f32_dpp v212, v212, v212 quad_perm:[2,3,0,1] row_mask:0xf bank_mask:0xf bound_ctrl:1
	v_add_f32_dpp v208, v208, v208 row_ror:4 row_mask:0xf bank_mask:0xf bound_ctrl:1
	v_add_f32_dpp v209, v209, v209 row_ror:4 row_mask:0xf bank_mask:0xf bound_ctrl:1
	v_add_f32_dpp v210, v210, v210 row_ror:4 row_mask:0xf bank_mask:0xf bound_ctrl:1
	v_add_f32_dpp v212, v212, v212 row_ror:4 row_mask:0xf bank_mask:0xf bound_ctrl:1
	v_add_f32_dpp v208, v208, v208 row_ror:8 row_mask:0xf bank_mask:0xf bound_ctrl:1
	v_add_f32_dpp v209, v209, v209 row_ror:8 row_mask:0xf bank_mask:0xf bound_ctrl:1
	v_add_f32_dpp v210, v210, v210 row_ror:8 row_mask:0xf bank_mask:0xf bound_ctrl:1
	v_add_f32_dpp v212, v212, v212 row_ror:8 row_mask:0xf bank_mask:0xf bound_ctrl:1
	v_max_f32_e32 v218, v208, v200
	v_sub_f32_e32 v217, v200, v218
	v_sub_f32_e32 v208, v208, v218
	v_mul_f32_e32 v217, 0x3fb8aa3b, v217
	v_mul_f32_e32 v208, 0x3fb8aa3b, v208
	v_exp_f32_e32 v217, v217
	v_exp_f32_e32 v208, v208
	v_mov_b32_e32 v200, v218
	s_waitcnt vmcnt(38)
	v_fma_f32 v204, v204, v217, v208
	v_mul_f32_e32 v180, v180, v217
	v_mul_f32_e32 v181, v181, v217
	v_mul_f32_e32 v182, v182, v217
	v_mul_f32_e32 v183, v183, v217
	v_fmac_f32_e32 v180, v208, v112
	v_fmac_f32_e32 v181, v208, v113
	v_fmac_f32_e32 v182, v208, v114
	v_fmac_f32_e32 v183, v208, v115
	v_max_f32_e32 v218, v209, v201
	v_sub_f32_e32 v217, v201, v218
	v_sub_f32_e32 v209, v209, v218
	v_mul_f32_e32 v217, 0x3fb8aa3b, v217
	v_mul_f32_e32 v209, 0x3fb8aa3b, v209
	v_exp_f32_e32 v217, v217
	v_exp_f32_e32 v209, v209
	v_mov_b32_e32 v201, v218
	s_waitcnt vmcnt(36)
	v_fma_f32 v205, v205, v217, v209
	v_mul_f32_e32 v184, v184, v217
	v_mul_f32_e32 v185, v185, v217
	v_mul_f32_e32 v186, v186, v217
	v_mul_f32_e32 v187, v187, v217
	v_fmac_f32_e32 v184, v209, v116
	v_fmac_f32_e32 v185, v209, v117
	v_fmac_f32_e32 v186, v209, v118
	v_fmac_f32_e32 v187, v209, v119
	v_max_f32_e32 v218, v210, v202
	v_sub_f32_e32 v217, v202, v218
	v_sub_f32_e32 v210, v210, v218
	v_mul_f32_e32 v217, 0x3fb8aa3b, v217
	v_mul_f32_e32 v210, 0x3fb8aa3b, v210
	v_exp_f32_e32 v217, v217
	v_exp_f32_e32 v210, v210
	v_mov_b32_e32 v202, v218
	s_waitcnt vmcnt(34)
	v_fma_f32 v206, v206, v217, v210
	v_mul_f32_e32 v188, v188, v217
	v_mul_f32_e32 v189, v189, v217
	v_mul_f32_e32 v190, v190, v217
	v_mul_f32_e32 v191, v191, v217
	v_fmac_f32_e32 v188, v210, v120
	v_fmac_f32_e32 v189, v210, v121
	v_fmac_f32_e32 v190, v210, v122
	v_fmac_f32_e32 v191, v210, v123
	v_max_f32_e32 v218, v212, v203
	v_sub_f32_e32 v217, v203, v218
	v_sub_f32_e32 v212, v212, v218
	v_mul_f32_e32 v217, 0x3fb8aa3b, v217
	v_mul_f32_e32 v212, 0x3fb8aa3b, v212
	v_exp_f32_e32 v217, v217
	v_exp_f32_e32 v212, v212
	v_mov_b32_e32 v203, v218
	s_waitcnt vmcnt(32)
	v_fma_f32 v207, v207, v217, v212
	v_mul_f32_e32 v196, v196, v217
	v_mul_f32_e32 v197, v197, v217
	v_mul_f32_e32 v198, v198, v217
	v_mul_f32_e32 v199, v199, v217
	v_fmac_f32_e32 v196, v212, v124
	v_fmac_f32_e32 v197, v212, v125
	v_fmac_f32_e32 v198, v212, v126
	v_fmac_f32_e32 v199, v212, v127
	s_sub_u32 s62, s62, s64
	s_subb_u32 s63, s63, 0
	s_add_u32 s42, s62, 0x1000
	s_addc_u32 s43, s63, 0
	global_load_dwordx4 v[96:99], v214, s[62:63] nt
	global_load_dwordx4 v[112:115], v214, s[62:63] offset:512 nt
	global_load_dwordx4 v[100:103], v214, s[62:63] offset:2048 nt
	global_load_dwordx4 v[116:119], v214, s[62:63] offset:2560 nt
	global_load_dwordx4 v[104:107], v214, s[42:43] nt
	global_load_dwordx4 v[120:123], v214, s[42:43] offset:512 nt
	global_load_dwordx4 v[108:111], v214, s[42:43] offset:2048 nt
	global_load_dwordx4 v[124:127], v214, s[42:43] offset:2560 nt
	s_waitcnt vmcnt(39)
	v_mul_f32_e32 v208, v164, v128
	v_fmac_f32_e32 v208, v165, v129
	v_fmac_f32_e32 v208, v166, v130
	v_fmac_f32_e32 v208, v167, v131
	s_waitcnt vmcnt(37)
	v_mul_f32_e32 v209, v168, v132
	v_fmac_f32_e32 v209, v169, v133
	v_fmac_f32_e32 v209, v170, v134
	v_fmac_f32_e32 v209, v171, v135
	s_waitcnt vmcnt(35)
	v_mul_f32_e32 v210, v172, v138
	v_fmac_f32_e32 v210, v173, v139
	v_fmac_f32_e32 v210, v174, v140
	v_fmac_f32_e32 v210, v175, v141
	s_waitcnt vmcnt(33)
	v_mul_f32_e32 v212, v176, v142
	v_fmac_f32_e32 v212, v177, v143
	v_fmac_f32_e32 v212, v178, v144
	v_fmac_f32_e32 v212, v179, v145
	v_add_f32_dpp v208, v208, v208 quad_perm:[1,0,3,2] row_mask:0xf bank_mask:0xf bound_ctrl:1
	v_add_f32_dpp v209, v209, v209 quad_perm:[1,0,3,2] row_mask:0xf bank_mask:0xf bound_ctrl:1
	v_add_f32_dpp v210, v210, v210 quad_perm:[1,0,3,2] row_mask:0xf bank_mask:0xf bound_ctrl:1
	v_add_f32_dpp v212, v212, v212 quad_perm:[1,0,3,2] row_mask:0xf bank_mask:0xf bound_ctrl:1
	v_add_f32_dpp v208, v208, v208 quad_perm:[2,3,0,1] row_mask:0xf bank_mask:0xf bound_ctrl:1
	v_add_f32_dpp v209, v209, v209 quad_perm:[2,3,0,1] row_mask:0xf bank_mask:0xf bound_ctrl:1
	v_add_f32_dpp v210, v210, v210 quad_perm:[2,3,0,1] row_mask:0xf bank_mask:0xf bound_ctrl:1
	v_add_f32_dpp v212, v212, v212 quad_perm:[2,3,0,1] row_mask:0xf bank_mask:0xf bound_ctrl:1
	v_add_f32_dpp v208, v208, v208 row_ror:4 row_mask:0xf bank_mask:0xf bound_ctrl:1
	v_add_f32_dpp v209, v209, v209 row_ror:4 row_mask:0xf bank_mask:0xf bound_ctrl:1
	v_add_f32_dpp v210, v210, v210 row_ror:4 row_mask:0xf bank_mask:0xf bound_ctrl:1
	v_add_f32_dpp v212, v212, v212 row_ror:4 row_mask:0xf bank_mask:0xf bound_ctrl:1
	v_add_f32_dpp v208, v208, v208 row_ror:8 row_mask:0xf bank_mask:0xf bound_ctrl:1
	v_add_f32_dpp v209, v209, v209 row_ror:8 row_mask:0xf bank_mask:0xf bound_ctrl:1
	v_add_f32_dpp v210, v210, v210 row_ror:8 row_mask:0xf bank_mask:0xf bound_ctrl:1
	v_add_f32_dpp v212, v212, v212 row_ror:8 row_mask:0xf bank_mask:0xf bound_ctrl:1
	v_max_f32_e32 v218, v208, v200
	v_sub_f32_e32 v217, v200, v218
	v_sub_f32_e32 v208, v208, v218
	v_mul_f32_e32 v217, 0x3fb8aa3b, v217
	v_mul_f32_e32 v208, 0x3fb8aa3b, v208
	v_exp_f32_e32 v217, v217
	v_exp_f32_e32 v208, v208
	v_mov_b32_e32 v200, v218
	s_waitcnt vmcnt(38)
	v_fma_f32 v204, v204, v217, v208
	v_mul_f32_e32 v180, v180, v217
	v_mul_f32_e32 v181, v181, v217
	v_mul_f32_e32 v182, v182, v217
	v_mul_f32_e32 v183, v183, v217
	v_fmac_f32_e32 v180, v208, v146
	v_fmac_f32_e32 v181, v208, v147
	v_fmac_f32_e32 v182, v208, v148
	v_fmac_f32_e32 v183, v208, v149
	v_max_f32_e32 v218, v209, v201
	v_sub_f32_e32 v217, v201, v218
	v_sub_f32_e32 v209, v209, v218
	v_mul_f32_e32 v217, 0x3fb8aa3b, v217
	v_mul_f32_e32 v209, 0x3fb8aa3b, v209
	v_exp_f32_e32 v217, v217
	v_exp_f32_e32 v209, v209
	v_mov_b32_e32 v201, v218
	s_waitcnt vmcnt(36)
	v_fma_f32 v205, v205, v217, v209
	v_mul_f32_e32 v184, v184, v217
	v_mul_f32_e32 v185, v185, v217
	v_mul_f32_e32 v186, v186, v217
	v_mul_f32_e32 v187, v187, v217
	v_fmac_f32_e32 v184, v209, v150
	v_fmac_f32_e32 v185, v209, v151
	v_fmac_f32_e32 v186, v209, v152
	v_fmac_f32_e32 v187, v209, v153
	v_max_f32_e32 v218, v210, v202
	v_sub_f32_e32 v217, v202, v218
	v_sub_f32_e32 v210, v210, v218
	v_mul_f32_e32 v217, 0x3fb8aa3b, v217
	v_mul_f32_e32 v210, 0x3fb8aa3b, v210
	v_exp_f32_e32 v217, v217
	v_exp_f32_e32 v210, v210
	v_mov_b32_e32 v202, v218
	s_waitcnt vmcnt(34)
	v_fma_f32 v206, v206, v217, v210
	v_mul_f32_e32 v188, v188, v217
	v_mul_f32_e32 v189, v189, v217
	v_mul_f32_e32 v190, v190, v217
	v_mul_f32_e32 v191, v191, v217
	v_fmac_f32_e32 v188, v210, v154
	v_fmac_f32_e32 v189, v210, v155
	v_fmac_f32_e32 v190, v210, v156
	v_fmac_f32_e32 v191, v210, v157
	v_max_f32_e32 v218, v212, v203
	v_sub_f32_e32 v217, v203, v218
	v_sub_f32_e32 v212, v212, v218
	v_mul_f32_e32 v217, 0x3fb8aa3b, v217
	v_mul_f32_e32 v212, 0x3fb8aa3b, v212
	v_exp_f32_e32 v217, v217
	v_exp_f32_e32 v212, v212
	v_mov_b32_e32 v203, v218
	s_waitcnt vmcnt(32)
	v_fma_f32 v207, v207, v217, v212
	v_mul_f32_e32 v196, v196, v217
	v_mul_f32_e32 v197, v197, v217
	v_mul_f32_e32 v198, v198, v217
	v_mul_f32_e32 v199, v199, v217
	v_fmac_f32_e32 v196, v212, v158
	v_fmac_f32_e32 v197, v212, v159
	v_fmac_f32_e32 v198, v212, v160
	v_fmac_f32_e32 v199, v212, v161
	s_sub_u32 s62, s62, s64
	s_subb_u32 s63, s63, 0
	s_add_u32 s42, s62, 0x1000
	s_addc_u32 s43, s63, 0
	global_load_dwordx4 v[128:131], v214, s[62:63] nt
	global_load_dwordx4 v[146:149], v214, s[62:63] offset:512 nt
	global_load_dwordx4 v[132:135], v214, s[62:63] offset:2048 nt
	global_load_dwordx4 v[150:153], v214, s[62:63] offset:2560 nt
	global_load_dwordx4 v[138:141], v214, s[42:43] nt
	global_load_dwordx4 v[154:157], v214, s[42:43] offset:512 nt
	global_load_dwordx4 v[142:145], v214, s[42:43] offset:2048 nt
	global_load_dwordx4 v[158:161], v214, s[42:43] offset:2560 nt
	s_waitcnt vmcnt(39)
	v_mul_f32_e32 v208, v164, v0
	v_fmac_f32_e32 v208, v165, v1
	v_fmac_f32_e32 v208, v166, v2
	v_fmac_f32_e32 v208, v167, v3
	s_waitcnt vmcnt(37)
	v_mul_f32_e32 v209, v168, v4
	v_fmac_f32_e32 v209, v169, v5
	v_fmac_f32_e32 v209, v170, v6
	v_fmac_f32_e32 v209, v171, v7
	s_waitcnt vmcnt(35)
	v_mul_f32_e32 v210, v172, v8
	v_fmac_f32_e32 v210, v173, v9
	v_fmac_f32_e32 v210, v174, v10
	v_fmac_f32_e32 v210, v175, v11
	s_waitcnt vmcnt(33)
	v_mul_f32_e32 v212, v176, v12
	v_fmac_f32_e32 v212, v177, v13
	v_fmac_f32_e32 v212, v178, v14
	v_fmac_f32_e32 v212, v179, v15
	v_add_f32_dpp v208, v208, v208 quad_perm:[1,0,3,2] row_mask:0xf bank_mask:0xf bound_ctrl:1
	v_add_f32_dpp v209, v209, v209 quad_perm:[1,0,3,2] row_mask:0xf bank_mask:0xf bound_ctrl:1
	v_add_f32_dpp v210, v210, v210 quad_perm:[1,0,3,2] row_mask:0xf bank_mask:0xf bound_ctrl:1
	v_add_f32_dpp v212, v212, v212 quad_perm:[1,0,3,2] row_mask:0xf bank_mask:0xf bound_ctrl:1
	v_add_f32_dpp v208, v208, v208 quad_perm:[2,3,0,1] row_mask:0xf bank_mask:0xf bound_ctrl:1
	v_add_f32_dpp v209, v209, v209 quad_perm:[2,3,0,1] row_mask:0xf bank_mask:0xf bound_ctrl:1
	v_add_f32_dpp v210, v210, v210 quad_perm:[2,3,0,1] row_mask:0xf bank_mask:0xf bound_ctrl:1
	v_add_f32_dpp v212, v212, v212 quad_perm:[2,3,0,1] row_mask:0xf bank_mask:0xf bound_ctrl:1
	v_add_f32_dpp v208, v208, v208 row_ror:4 row_mask:0xf bank_mask:0xf bound_ctrl:1
	v_add_f32_dpp v209, v209, v209 row_ror:4 row_mask:0xf bank_mask:0xf bound_ctrl:1
	v_add_f32_dpp v210, v210, v210 row_ror:4 row_mask:0xf bank_mask:0xf bound_ctrl:1
	v_add_f32_dpp v212, v212, v212 row_ror:4 row_mask:0xf bank_mask:0xf bound_ctrl:1
	v_add_f32_dpp v208, v208, v208 row_ror:8 row_mask:0xf bank_mask:0xf bound_ctrl:1
	v_add_f32_dpp v209, v209, v209 row_ror:8 row_mask:0xf bank_mask:0xf bound_ctrl:1
	v_add_f32_dpp v210, v210, v210 row_ror:8 row_mask:0xf bank_mask:0xf bound_ctrl:1
	v_add_f32_dpp v212, v212, v212 row_ror:8 row_mask:0xf bank_mask:0xf bound_ctrl:1
	v_max_f32_e32 v218, v208, v200
	v_sub_f32_e32 v217, v200, v218
	v_sub_f32_e32 v208, v208, v218
	v_mul_f32_e32 v217, 0x3fb8aa3b, v217
	v_mul_f32_e32 v208, 0x3fb8aa3b, v208
	v_exp_f32_e32 v217, v217
	v_exp_f32_e32 v208, v208
	v_mov_b32_e32 v200, v218
	s_waitcnt vmcnt(38)
	v_fma_f32 v204, v204, v217, v208
	v_mul_f32_e32 v180, v180, v217
	v_mul_f32_e32 v181, v181, v217
	v_mul_f32_e32 v182, v182, v217
	v_mul_f32_e32 v183, v183, v217
	v_fmac_f32_e32 v180, v208, v16
	v_fmac_f32_e32 v181, v208, v17
	v_fmac_f32_e32 v182, v208, v18
	v_fmac_f32_e32 v183, v208, v19
	v_max_f32_e32 v218, v209, v201
	v_sub_f32_e32 v217, v201, v218
	v_sub_f32_e32 v209, v209, v218
	v_mul_f32_e32 v217, 0x3fb8aa3b, v217
	v_mul_f32_e32 v209, 0x3fb8aa3b, v209
	v_exp_f32_e32 v217, v217
	v_exp_f32_e32 v209, v209
	v_mov_b32_e32 v201, v218
	s_waitcnt vmcnt(36)
	v_fma_f32 v205, v205, v217, v209
	v_mul_f32_e32 v184, v184, v217
	v_mul_f32_e32 v185, v185, v217
	v_mul_f32_e32 v186, v186, v217
	v_mul_f32_e32 v187, v187, v217
	v_fmac_f32_e32 v184, v209, v20
	v_fmac_f32_e32 v185, v209, v21
	v_fmac_f32_e32 v186, v209, v22
	v_fmac_f32_e32 v187, v209, v23
	v_max_f32_e32 v218, v210, v202
	v_sub_f32_e32 v217, v202, v218
	v_sub_f32_e32 v210, v210, v218
	v_mul_f32_e32 v217, 0x3fb8aa3b, v217
	v_mul_f32_e32 v210, 0x3fb8aa3b, v210
	v_exp_f32_e32 v217, v217
	v_exp_f32_e32 v210, v210
	v_mov_b32_e32 v202, v218
	s_waitcnt vmcnt(34)
	v_fma_f32 v206, v206, v217, v210
	v_mul_f32_e32 v188, v188, v217
	v_mul_f32_e32 v189, v189, v217
	v_mul_f32_e32 v190, v190, v217
	v_mul_f32_e32 v191, v191, v217
	v_fmac_f32_e32 v188, v210, v24
	v_fmac_f32_e32 v189, v210, v25
	v_fmac_f32_e32 v190, v210, v26
	v_fmac_f32_e32 v191, v210, v27
	v_max_f32_e32 v218, v212, v203
	v_sub_f32_e32 v217, v203, v218
	v_sub_f32_e32 v212, v212, v218
	v_mul_f32_e32 v217, 0x3fb8aa3b, v217
	v_mul_f32_e32 v212, 0x3fb8aa3b, v212
	v_exp_f32_e32 v217, v217
	v_exp_f32_e32 v212, v212
	v_mov_b32_e32 v203, v218
	s_waitcnt vmcnt(32)
	v_fma_f32 v207, v207, v217, v212
	v_mul_f32_e32 v196, v196, v217
	v_mul_f32_e32 v197, v197, v217
	v_mul_f32_e32 v198, v198, v217
	v_mul_f32_e32 v199, v199, v217
	v_fmac_f32_e32 v196, v212, v28
	v_fmac_f32_e32 v197, v212, v29
	v_fmac_f32_e32 v198, v212, v30
	v_fmac_f32_e32 v199, v212, v31
	s_sub_u32 s62, s62, s64
	s_subb_u32 s63, s63, 0
	s_add_u32 s42, s62, 0x1000
	s_addc_u32 s43, s63, 0
	global_load_dwordx4 v[0:3], v214, s[62:63] nt
	global_load_dwordx4 v[16:19], v214, s[62:63] offset:512 nt
	global_load_dwordx4 v[4:7], v214, s[62:63] offset:2048 nt
	global_load_dwordx4 v[20:23], v214, s[62:63] offset:2560 nt
	global_load_dwordx4 v[8:11], v214, s[42:43] nt
	global_load_dwordx4 v[24:27], v214, s[42:43] offset:512 nt
	global_load_dwordx4 v[12:15], v214, s[42:43] offset:2048 nt
	global_load_dwordx4 v[28:31], v214, s[42:43] offset:2560 nt
	s_waitcnt vmcnt(39)
	v_mul_f32_e32 v208, v164, v32
	v_fmac_f32_e32 v208, v165, v33
	v_fmac_f32_e32 v208, v166, v34
	v_fmac_f32_e32 v208, v167, v35
	s_waitcnt vmcnt(37)
	v_mul_f32_e32 v209, v168, v36
	v_fmac_f32_e32 v209, v169, v37
	v_fmac_f32_e32 v209, v170, v38
	v_fmac_f32_e32 v209, v171, v39
	s_waitcnt vmcnt(35)
	v_mul_f32_e32 v210, v172, v40
	v_fmac_f32_e32 v210, v173, v41
	v_fmac_f32_e32 v210, v174, v42
	v_fmac_f32_e32 v210, v175, v43
	s_waitcnt vmcnt(33)
	v_mul_f32_e32 v212, v176, v44
	v_fmac_f32_e32 v212, v177, v45
	v_fmac_f32_e32 v212, v178, v46
	v_fmac_f32_e32 v212, v179, v47
	v_add_f32_dpp v208, v208, v208 quad_perm:[1,0,3,2] row_mask:0xf bank_mask:0xf bound_ctrl:1
	v_add_f32_dpp v209, v209, v209 quad_perm:[1,0,3,2] row_mask:0xf bank_mask:0xf bound_ctrl:1
	v_add_f32_dpp v210, v210, v210 quad_perm:[1,0,3,2] row_mask:0xf bank_mask:0xf bound_ctrl:1
	v_add_f32_dpp v212, v212, v212 quad_perm:[1,0,3,2] row_mask:0xf bank_mask:0xf bound_ctrl:1
	v_add_f32_dpp v208, v208, v208 quad_perm:[2,3,0,1] row_mask:0xf bank_mask:0xf bound_ctrl:1
	v_add_f32_dpp v209, v209, v209 quad_perm:[2,3,0,1] row_mask:0xf bank_mask:0xf bound_ctrl:1
	v_add_f32_dpp v210, v210, v210 quad_perm:[2,3,0,1] row_mask:0xf bank_mask:0xf bound_ctrl:1
	v_add_f32_dpp v212, v212, v212 quad_perm:[2,3,0,1] row_mask:0xf bank_mask:0xf bound_ctrl:1
	v_add_f32_dpp v208, v208, v208 row_ror:4 row_mask:0xf bank_mask:0xf bound_ctrl:1
	v_add_f32_dpp v209, v209, v209 row_ror:4 row_mask:0xf bank_mask:0xf bound_ctrl:1
	v_add_f32_dpp v210, v210, v210 row_ror:4 row_mask:0xf bank_mask:0xf bound_ctrl:1
	v_add_f32_dpp v212, v212, v212 row_ror:4 row_mask:0xf bank_mask:0xf bound_ctrl:1
	v_add_f32_dpp v208, v208, v208 row_ror:8 row_mask:0xf bank_mask:0xf bound_ctrl:1
	v_add_f32_dpp v209, v209, v209 row_ror:8 row_mask:0xf bank_mask:0xf bound_ctrl:1
	v_add_f32_dpp v210, v210, v210 row_ror:8 row_mask:0xf bank_mask:0xf bound_ctrl:1
	v_add_f32_dpp v212, v212, v212 row_ror:8 row_mask:0xf bank_mask:0xf bound_ctrl:1
	v_max_f32_e32 v218, v208, v200
	v_sub_f32_e32 v217, v200, v218
	v_sub_f32_e32 v208, v208, v218
	v_mul_f32_e32 v217, 0x3fb8aa3b, v217
	v_mul_f32_e32 v208, 0x3fb8aa3b, v208
	v_exp_f32_e32 v217, v217
	v_exp_f32_e32 v208, v208
	v_mov_b32_e32 v200, v218
	s_waitcnt vmcnt(38)
	v_fma_f32 v204, v204, v217, v208
	v_mul_f32_e32 v180, v180, v217
	v_mul_f32_e32 v181, v181, v217
	v_mul_f32_e32 v182, v182, v217
	v_mul_f32_e32 v183, v183, v217
	v_fmac_f32_e32 v180, v208, v48
	v_fmac_f32_e32 v181, v208, v49
	v_fmac_f32_e32 v182, v208, v50
	v_fmac_f32_e32 v183, v208, v51
	v_max_f32_e32 v218, v209, v201
	v_sub_f32_e32 v217, v201, v218
	v_sub_f32_e32 v209, v209, v218
	v_mul_f32_e32 v217, 0x3fb8aa3b, v217
	v_mul_f32_e32 v209, 0x3fb8aa3b, v209
	v_exp_f32_e32 v217, v217
	v_exp_f32_e32 v209, v209
	v_mov_b32_e32 v201, v218
	s_waitcnt vmcnt(36)
	v_fma_f32 v205, v205, v217, v209
	v_mul_f32_e32 v184, v184, v217
	v_mul_f32_e32 v185, v185, v217
	v_mul_f32_e32 v186, v186, v217
	v_mul_f32_e32 v187, v187, v217
	v_fmac_f32_e32 v184, v209, v52
	v_fmac_f32_e32 v185, v209, v53
	v_fmac_f32_e32 v186, v209, v54
	v_fmac_f32_e32 v187, v209, v55
	v_max_f32_e32 v218, v210, v202
	v_sub_f32_e32 v217, v202, v218
	v_sub_f32_e32 v210, v210, v218
	v_mul_f32_e32 v217, 0x3fb8aa3b, v217
	v_mul_f32_e32 v210, 0x3fb8aa3b, v210
	v_exp_f32_e32 v217, v217
	v_exp_f32_e32 v210, v210
	v_mov_b32_e32 v202, v218
	s_waitcnt vmcnt(34)
	v_fma_f32 v206, v206, v217, v210
	v_mul_f32_e32 v188, v188, v217
	v_mul_f32_e32 v189, v189, v217
	v_mul_f32_e32 v190, v190, v217
	v_mul_f32_e32 v191, v191, v217
	v_fmac_f32_e32 v188, v210, v56
	v_fmac_f32_e32 v189, v210, v57
	v_fmac_f32_e32 v190, v210, v58
	v_fmac_f32_e32 v191, v210, v59
	v_max_f32_e32 v218, v212, v203
	v_sub_f32_e32 v217, v203, v218
	v_sub_f32_e32 v212, v212, v218
	v_mul_f32_e32 v217, 0x3fb8aa3b, v217
	v_mul_f32_e32 v212, 0x3fb8aa3b, v212
	v_exp_f32_e32 v217, v217
	v_exp_f32_e32 v212, v212
	v_mov_b32_e32 v203, v218
	s_waitcnt vmcnt(32)
	v_fma_f32 v207, v207, v217, v212
	v_mul_f32_e32 v196, v196, v217
	v_mul_f32_e32 v197, v197, v217
	v_mul_f32_e32 v198, v198, v217
	v_mul_f32_e32 v199, v199, v217
	v_fmac_f32_e32 v196, v212, v60
	v_fmac_f32_e32 v197, v212, v61
	v_fmac_f32_e32 v198, v212, v62
	v_fmac_f32_e32 v199, v212, v63
	s_sub_u32 s62, s62, s64
	s_subb_u32 s63, s63, 0
	s_add_u32 s42, s62, 0x1000
	s_addc_u32 s43, s63, 0
	global_load_dwordx4 v[32:35], v214, s[62:63] nt
	global_load_dwordx4 v[48:51], v214, s[62:63] offset:512 nt
	global_load_dwordx4 v[36:39], v214, s[62:63] offset:2048 nt
	global_load_dwordx4 v[52:55], v214, s[62:63] offset:2560 nt
	global_load_dwordx4 v[40:43], v214, s[42:43] nt
	global_load_dwordx4 v[56:59], v214, s[42:43] offset:512 nt
	global_load_dwordx4 v[44:47], v214, s[42:43] offset:2048 nt
	global_load_dwordx4 v[60:63], v214, s[42:43] offset:2560 nt
	s_waitcnt vmcnt(39)
	v_mul_f32_e32 v208, v164, v64
	v_fmac_f32_e32 v208, v165, v65
	v_fmac_f32_e32 v208, v166, v66
	v_fmac_f32_e32 v208, v167, v67
	s_waitcnt vmcnt(37)
	v_mul_f32_e32 v209, v168, v68
	v_fmac_f32_e32 v209, v169, v69
	v_fmac_f32_e32 v209, v170, v70
	v_fmac_f32_e32 v209, v171, v71
	s_waitcnt vmcnt(35)
	v_mul_f32_e32 v210, v172, v72
	v_fmac_f32_e32 v210, v173, v73
	v_fmac_f32_e32 v210, v174, v74
	v_fmac_f32_e32 v210, v175, v75
	s_waitcnt vmcnt(33)
	v_mul_f32_e32 v212, v176, v76
	v_fmac_f32_e32 v212, v177, v77
	v_fmac_f32_e32 v212, v178, v78
	v_fmac_f32_e32 v212, v179, v79
	v_add_f32_dpp v208, v208, v208 quad_perm:[1,0,3,2] row_mask:0xf bank_mask:0xf bound_ctrl:1
	v_add_f32_dpp v209, v209, v209 quad_perm:[1,0,3,2] row_mask:0xf bank_mask:0xf bound_ctrl:1
	v_add_f32_dpp v210, v210, v210 quad_perm:[1,0,3,2] row_mask:0xf bank_mask:0xf bound_ctrl:1
	v_add_f32_dpp v212, v212, v212 quad_perm:[1,0,3,2] row_mask:0xf bank_mask:0xf bound_ctrl:1
	v_add_f32_dpp v208, v208, v208 quad_perm:[2,3,0,1] row_mask:0xf bank_mask:0xf bound_ctrl:1
	v_add_f32_dpp v209, v209, v209 quad_perm:[2,3,0,1] row_mask:0xf bank_mask:0xf bound_ctrl:1
	v_add_f32_dpp v210, v210, v210 quad_perm:[2,3,0,1] row_mask:0xf bank_mask:0xf bound_ctrl:1
	v_add_f32_dpp v212, v212, v212 quad_perm:[2,3,0,1] row_mask:0xf bank_mask:0xf bound_ctrl:1
	v_add_f32_dpp v208, v208, v208 row_ror:4 row_mask:0xf bank_mask:0xf bound_ctrl:1
	v_add_f32_dpp v209, v209, v209 row_ror:4 row_mask:0xf bank_mask:0xf bound_ctrl:1
	v_add_f32_dpp v210, v210, v210 row_ror:4 row_mask:0xf bank_mask:0xf bound_ctrl:1
	v_add_f32_dpp v212, v212, v212 row_ror:4 row_mask:0xf bank_mask:0xf bound_ctrl:1
	v_add_f32_dpp v208, v208, v208 row_ror:8 row_mask:0xf bank_mask:0xf bound_ctrl:1
	v_add_f32_dpp v209, v209, v209 row_ror:8 row_mask:0xf bank_mask:0xf bound_ctrl:1
	v_add_f32_dpp v210, v210, v210 row_ror:8 row_mask:0xf bank_mask:0xf bound_ctrl:1
	v_add_f32_dpp v212, v212, v212 row_ror:8 row_mask:0xf bank_mask:0xf bound_ctrl:1
	v_max_f32_e32 v218, v208, v200
	v_sub_f32_e32 v217, v200, v218
	v_sub_f32_e32 v208, v208, v218
	v_mul_f32_e32 v217, 0x3fb8aa3b, v217
	v_mul_f32_e32 v208, 0x3fb8aa3b, v208
	v_exp_f32_e32 v217, v217
	v_exp_f32_e32 v208, v208
	v_mov_b32_e32 v200, v218
	s_waitcnt vmcnt(38)
	v_fma_f32 v204, v204, v217, v208
	v_mul_f32_e32 v180, v180, v217
	v_mul_f32_e32 v181, v181, v217
	v_mul_f32_e32 v182, v182, v217
	v_mul_f32_e32 v183, v183, v217
	v_fmac_f32_e32 v180, v208, v80
	v_fmac_f32_e32 v181, v208, v81
	v_fmac_f32_e32 v182, v208, v82
	v_fmac_f32_e32 v183, v208, v83
	v_max_f32_e32 v218, v209, v201
	v_sub_f32_e32 v217, v201, v218
	v_sub_f32_e32 v209, v209, v218
	v_mul_f32_e32 v217, 0x3fb8aa3b, v217
	v_mul_f32_e32 v209, 0x3fb8aa3b, v209
	v_exp_f32_e32 v217, v217
	v_exp_f32_e32 v209, v209
	v_mov_b32_e32 v201, v218
	s_waitcnt vmcnt(36)
	v_fma_f32 v205, v205, v217, v209
	v_mul_f32_e32 v184, v184, v217
	v_mul_f32_e32 v185, v185, v217
	v_mul_f32_e32 v186, v186, v217
	v_mul_f32_e32 v187, v187, v217
	v_fmac_f32_e32 v184, v209, v84
	v_fmac_f32_e32 v185, v209, v85
	v_fmac_f32_e32 v186, v209, v86
	v_fmac_f32_e32 v187, v209, v87
	v_max_f32_e32 v218, v210, v202
	v_sub_f32_e32 v217, v202, v218
	v_sub_f32_e32 v210, v210, v218
	v_mul_f32_e32 v217, 0x3fb8aa3b, v217
	v_mul_f32_e32 v210, 0x3fb8aa3b, v210
	v_exp_f32_e32 v217, v217
	v_exp_f32_e32 v210, v210
	v_mov_b32_e32 v202, v218
	s_waitcnt vmcnt(34)
	v_fma_f32 v206, v206, v217, v210
	v_mul_f32_e32 v188, v188, v217
	v_mul_f32_e32 v189, v189, v217
	v_mul_f32_e32 v190, v190, v217
	v_mul_f32_e32 v191, v191, v217
	v_fmac_f32_e32 v188, v210, v88
	v_fmac_f32_e32 v189, v210, v89
	v_fmac_f32_e32 v190, v210, v90
	v_fmac_f32_e32 v191, v210, v91
	v_max_f32_e32 v218, v212, v203
	v_sub_f32_e32 v217, v203, v218
	v_sub_f32_e32 v212, v212, v218
	v_mul_f32_e32 v217, 0x3fb8aa3b, v217
	v_mul_f32_e32 v212, 0x3fb8aa3b, v212
	v_exp_f32_e32 v217, v217
	v_exp_f32_e32 v212, v212
	v_mov_b32_e32 v203, v218
	s_waitcnt vmcnt(32)
	v_fma_f32 v207, v207, v217, v212
	v_mul_f32_e32 v196, v196, v217
	v_mul_f32_e32 v197, v197, v217
	v_mul_f32_e32 v198, v198, v217
	v_mul_f32_e32 v199, v199, v217
	v_fmac_f32_e32 v196, v212, v92
	v_fmac_f32_e32 v197, v212, v93
	v_fmac_f32_e32 v198, v212, v94
	v_fmac_f32_e32 v199, v212, v95
	s_sub_u32 s62, s62, s64
	s_subb_u32 s63, s63, 0
	s_add_u32 s42, s62, 0x1000
	s_addc_u32 s43, s63, 0
	global_load_dwordx4 v[64:67], v214, s[62:63] nt
	global_load_dwordx4 v[80:83], v214, s[62:63] offset:512 nt
	global_load_dwordx4 v[68:71], v214, s[62:63] offset:2048 nt
	global_load_dwordx4 v[84:87], v214, s[62:63] offset:2560 nt
	global_load_dwordx4 v[72:75], v214, s[42:43] nt
	global_load_dwordx4 v[88:91], v214, s[42:43] offset:512 nt
	global_load_dwordx4 v[76:79], v214, s[42:43] offset:2048 nt
	global_load_dwordx4 v[92:95], v214, s[42:43] offset:2560 nt
	s_waitcnt vmcnt(39)
	v_mul_f32_e32 v208, v164, v96
	v_fmac_f32_e32 v208, v165, v97
	v_fmac_f32_e32 v208, v166, v98
	v_fmac_f32_e32 v208, v167, v99
	s_waitcnt vmcnt(37)
	v_mul_f32_e32 v209, v168, v100
	v_fmac_f32_e32 v209, v169, v101
	v_fmac_f32_e32 v209, v170, v102
	v_fmac_f32_e32 v209, v171, v103
	s_waitcnt vmcnt(35)
	v_mul_f32_e32 v210, v172, v104
	v_fmac_f32_e32 v210, v173, v105
	v_fmac_f32_e32 v210, v174, v106
	v_fmac_f32_e32 v210, v175, v107
	s_waitcnt vmcnt(33)
	v_mul_f32_e32 v212, v176, v108
	v_fmac_f32_e32 v212, v177, v109
	v_fmac_f32_e32 v212, v178, v110
	v_fmac_f32_e32 v212, v179, v111
	v_add_f32_dpp v208, v208, v208 quad_perm:[1,0,3,2] row_mask:0xf bank_mask:0xf bound_ctrl:1
	v_add_f32_dpp v209, v209, v209 quad_perm:[1,0,3,2] row_mask:0xf bank_mask:0xf bound_ctrl:1
	v_add_f32_dpp v210, v210, v210 quad_perm:[1,0,3,2] row_mask:0xf bank_mask:0xf bound_ctrl:1
	v_add_f32_dpp v212, v212, v212 quad_perm:[1,0,3,2] row_mask:0xf bank_mask:0xf bound_ctrl:1
	v_add_f32_dpp v208, v208, v208 quad_perm:[2,3,0,1] row_mask:0xf bank_mask:0xf bound_ctrl:1
	v_add_f32_dpp v209, v209, v209 quad_perm:[2,3,0,1] row_mask:0xf bank_mask:0xf bound_ctrl:1
	v_add_f32_dpp v210, v210, v210 quad_perm:[2,3,0,1] row_mask:0xf bank_mask:0xf bound_ctrl:1
	v_add_f32_dpp v212, v212, v212 quad_perm:[2,3,0,1] row_mask:0xf bank_mask:0xf bound_ctrl:1
	v_add_f32_dpp v208, v208, v208 row_ror:4 row_mask:0xf bank_mask:0xf bound_ctrl:1
	v_add_f32_dpp v209, v209, v209 row_ror:4 row_mask:0xf bank_mask:0xf bound_ctrl:1
	v_add_f32_dpp v210, v210, v210 row_ror:4 row_mask:0xf bank_mask:0xf bound_ctrl:1
	v_add_f32_dpp v212, v212, v212 row_ror:4 row_mask:0xf bank_mask:0xf bound_ctrl:1
	v_add_f32_dpp v208, v208, v208 row_ror:8 row_mask:0xf bank_mask:0xf bound_ctrl:1
	v_add_f32_dpp v209, v209, v209 row_ror:8 row_mask:0xf bank_mask:0xf bound_ctrl:1
	v_add_f32_dpp v210, v210, v210 row_ror:8 row_mask:0xf bank_mask:0xf bound_ctrl:1
	v_add_f32_dpp v212, v212, v212 row_ror:8 row_mask:0xf bank_mask:0xf bound_ctrl:1
	v_max_f32_e32 v218, v208, v200
	v_sub_f32_e32 v217, v200, v218
	v_sub_f32_e32 v208, v208, v218
	v_mul_f32_e32 v217, 0x3fb8aa3b, v217
	v_mul_f32_e32 v208, 0x3fb8aa3b, v208
	v_exp_f32_e32 v217, v217
	v_exp_f32_e32 v208, v208
	v_mov_b32_e32 v200, v218
	s_waitcnt vmcnt(38)
	v_fma_f32 v204, v204, v217, v208
	v_mul_f32_e32 v180, v180, v217
	v_mul_f32_e32 v181, v181, v217
	v_mul_f32_e32 v182, v182, v217
	v_mul_f32_e32 v183, v183, v217
	v_fmac_f32_e32 v180, v208, v112
	v_fmac_f32_e32 v181, v208, v113
	v_fmac_f32_e32 v182, v208, v114
	v_fmac_f32_e32 v183, v208, v115
	v_max_f32_e32 v218, v209, v201
	v_sub_f32_e32 v217, v201, v218
	v_sub_f32_e32 v209, v209, v218
	v_mul_f32_e32 v217, 0x3fb8aa3b, v217
	v_mul_f32_e32 v209, 0x3fb8aa3b, v209
	v_exp_f32_e32 v217, v217
	v_exp_f32_e32 v209, v209
	v_mov_b32_e32 v201, v218
	s_waitcnt vmcnt(36)
	v_fma_f32 v205, v205, v217, v209
	v_mul_f32_e32 v184, v184, v217
	v_mul_f32_e32 v185, v185, v217
	v_mul_f32_e32 v186, v186, v217
	v_mul_f32_e32 v187, v187, v217
	v_fmac_f32_e32 v184, v209, v116
	v_fmac_f32_e32 v185, v209, v117
	v_fmac_f32_e32 v186, v209, v118
	v_fmac_f32_e32 v187, v209, v119
	v_max_f32_e32 v218, v210, v202
	v_sub_f32_e32 v217, v202, v218
	v_sub_f32_e32 v210, v210, v218
	v_mul_f32_e32 v217, 0x3fb8aa3b, v217
	v_mul_f32_e32 v210, 0x3fb8aa3b, v210
	v_exp_f32_e32 v217, v217
	v_exp_f32_e32 v210, v210
	v_mov_b32_e32 v202, v218
	s_waitcnt vmcnt(34)
	v_fma_f32 v206, v206, v217, v210
	v_mul_f32_e32 v188, v188, v217
	v_mul_f32_e32 v189, v189, v217
	v_mul_f32_e32 v190, v190, v217
	v_mul_f32_e32 v191, v191, v217
	v_fmac_f32_e32 v188, v210, v120
	v_fmac_f32_e32 v189, v210, v121
	v_fmac_f32_e32 v190, v210, v122
	v_fmac_f32_e32 v191, v210, v123
	v_max_f32_e32 v218, v212, v203
	v_sub_f32_e32 v217, v203, v218
	v_sub_f32_e32 v212, v212, v218
	v_mul_f32_e32 v217, 0x3fb8aa3b, v217
	v_mul_f32_e32 v212, 0x3fb8aa3b, v212
	v_exp_f32_e32 v217, v217
	v_exp_f32_e32 v212, v212
	v_mov_b32_e32 v203, v218
	s_waitcnt vmcnt(32)
	v_fma_f32 v207, v207, v217, v212
	v_mul_f32_e32 v196, v196, v217
	v_mul_f32_e32 v197, v197, v217
	v_mul_f32_e32 v198, v198, v217
	v_mul_f32_e32 v199, v199, v217
	v_fmac_f32_e32 v196, v212, v124
	v_fmac_f32_e32 v197, v212, v125
	v_fmac_f32_e32 v198, v212, v126
	v_fmac_f32_e32 v199, v212, v127
	s_sub_u32 s62, s62, s64
	s_subb_u32 s63, s63, 0
	s_add_u32 s42, s62, 0x1000
	s_addc_u32 s43, s63, 0
	global_load_dwordx4 v[96:99], v214, s[62:63] nt
	global_load_dwordx4 v[112:115], v214, s[62:63] offset:512 nt
	global_load_dwordx4 v[100:103], v214, s[62:63] offset:2048 nt
	global_load_dwordx4 v[116:119], v214, s[62:63] offset:2560 nt
	global_load_dwordx4 v[104:107], v214, s[42:43] nt
	global_load_dwordx4 v[120:123], v214, s[42:43] offset:512 nt
	global_load_dwordx4 v[108:111], v214, s[42:43] offset:2048 nt
	global_load_dwordx4 v[124:127], v214, s[42:43] offset:2560 nt
	s_waitcnt vmcnt(39)
	v_mul_f32_e32 v208, v164, v128
	v_fmac_f32_e32 v208, v165, v129
	v_fmac_f32_e32 v208, v166, v130
	v_fmac_f32_e32 v208, v167, v131
	s_waitcnt vmcnt(37)
	v_mul_f32_e32 v209, v168, v132
	v_fmac_f32_e32 v209, v169, v133
	v_fmac_f32_e32 v209, v170, v134
	v_fmac_f32_e32 v209, v171, v135
	s_waitcnt vmcnt(35)
	v_mul_f32_e32 v210, v172, v138
	v_fmac_f32_e32 v210, v173, v139
	v_fmac_f32_e32 v210, v174, v140
	v_fmac_f32_e32 v210, v175, v141
	s_waitcnt vmcnt(33)
	v_mul_f32_e32 v212, v176, v142
	v_fmac_f32_e32 v212, v177, v143
	v_fmac_f32_e32 v212, v178, v144
	v_fmac_f32_e32 v212, v179, v145
	v_add_f32_dpp v208, v208, v208 quad_perm:[1,0,3,2] row_mask:0xf bank_mask:0xf bound_ctrl:1
	v_add_f32_dpp v209, v209, v209 quad_perm:[1,0,3,2] row_mask:0xf bank_mask:0xf bound_ctrl:1
	v_add_f32_dpp v210, v210, v210 quad_perm:[1,0,3,2] row_mask:0xf bank_mask:0xf bound_ctrl:1
	v_add_f32_dpp v212, v212, v212 quad_perm:[1,0,3,2] row_mask:0xf bank_mask:0xf bound_ctrl:1
	v_add_f32_dpp v208, v208, v208 quad_perm:[2,3,0,1] row_mask:0xf bank_mask:0xf bound_ctrl:1
	v_add_f32_dpp v209, v209, v209 quad_perm:[2,3,0,1] row_mask:0xf bank_mask:0xf bound_ctrl:1
	v_add_f32_dpp v210, v210, v210 quad_perm:[2,3,0,1] row_mask:0xf bank_mask:0xf bound_ctrl:1
	v_add_f32_dpp v212, v212, v212 quad_perm:[2,3,0,1] row_mask:0xf bank_mask:0xf bound_ctrl:1
	v_add_f32_dpp v208, v208, v208 row_ror:4 row_mask:0xf bank_mask:0xf bound_ctrl:1
	v_add_f32_dpp v209, v209, v209 row_ror:4 row_mask:0xf bank_mask:0xf bound_ctrl:1
	v_add_f32_dpp v210, v210, v210 row_ror:4 row_mask:0xf bank_mask:0xf bound_ctrl:1
	v_add_f32_dpp v212, v212, v212 row_ror:4 row_mask:0xf bank_mask:0xf bound_ctrl:1
	v_add_f32_dpp v208, v208, v208 row_ror:8 row_mask:0xf bank_mask:0xf bound_ctrl:1
	v_add_f32_dpp v209, v209, v209 row_ror:8 row_mask:0xf bank_mask:0xf bound_ctrl:1
	v_add_f32_dpp v210, v210, v210 row_ror:8 row_mask:0xf bank_mask:0xf bound_ctrl:1
	v_add_f32_dpp v212, v212, v212 row_ror:8 row_mask:0xf bank_mask:0xf bound_ctrl:1
	v_max_f32_e32 v218, v208, v200
	v_sub_f32_e32 v217, v200, v218
	v_sub_f32_e32 v208, v208, v218
	v_mul_f32_e32 v217, 0x3fb8aa3b, v217
	v_mul_f32_e32 v208, 0x3fb8aa3b, v208
	v_exp_f32_e32 v217, v217
	v_exp_f32_e32 v208, v208
	v_mov_b32_e32 v200, v218
	s_waitcnt vmcnt(38)
	v_fma_f32 v204, v204, v217, v208
	v_mul_f32_e32 v180, v180, v217
	v_mul_f32_e32 v181, v181, v217
	v_mul_f32_e32 v182, v182, v217
	v_mul_f32_e32 v183, v183, v217
	v_fmac_f32_e32 v180, v208, v146
	v_fmac_f32_e32 v181, v208, v147
	v_fmac_f32_e32 v182, v208, v148
	v_fmac_f32_e32 v183, v208, v149
	v_max_f32_e32 v218, v209, v201
	v_sub_f32_e32 v217, v201, v218
	v_sub_f32_e32 v209, v209, v218
	v_mul_f32_e32 v217, 0x3fb8aa3b, v217
	v_mul_f32_e32 v209, 0x3fb8aa3b, v209
	v_exp_f32_e32 v217, v217
	v_exp_f32_e32 v209, v209
	v_mov_b32_e32 v201, v218
	s_waitcnt vmcnt(36)
	v_fma_f32 v205, v205, v217, v209
	v_mul_f32_e32 v184, v184, v217
	v_mul_f32_e32 v185, v185, v217
	v_mul_f32_e32 v186, v186, v217
	v_mul_f32_e32 v187, v187, v217
	v_fmac_f32_e32 v184, v209, v150
	v_fmac_f32_e32 v185, v209, v151
	v_fmac_f32_e32 v186, v209, v152
	v_fmac_f32_e32 v187, v209, v153
	v_max_f32_e32 v218, v210, v202
	v_sub_f32_e32 v217, v202, v218
	v_sub_f32_e32 v210, v210, v218
	v_mul_f32_e32 v217, 0x3fb8aa3b, v217
	v_mul_f32_e32 v210, 0x3fb8aa3b, v210
	v_exp_f32_e32 v217, v217
	v_exp_f32_e32 v210, v210
	v_mov_b32_e32 v202, v218
	s_waitcnt vmcnt(34)
	v_fma_f32 v206, v206, v217, v210
	v_mul_f32_e32 v188, v188, v217
	v_mul_f32_e32 v189, v189, v217
	v_mul_f32_e32 v190, v190, v217
	v_mul_f32_e32 v191, v191, v217
	v_fmac_f32_e32 v188, v210, v154
	v_fmac_f32_e32 v189, v210, v155
	v_fmac_f32_e32 v190, v210, v156
	v_fmac_f32_e32 v191, v210, v157
	v_max_f32_e32 v218, v212, v203
	v_sub_f32_e32 v217, v203, v218
	v_sub_f32_e32 v212, v212, v218
	v_mul_f32_e32 v217, 0x3fb8aa3b, v217
	v_mul_f32_e32 v212, 0x3fb8aa3b, v212
	v_exp_f32_e32 v217, v217
	v_exp_f32_e32 v212, v212
	v_mov_b32_e32 v203, v218
	s_waitcnt vmcnt(32)
	v_fma_f32 v207, v207, v217, v212
	v_mul_f32_e32 v196, v196, v217
	v_mul_f32_e32 v197, v197, v217
	v_mul_f32_e32 v198, v198, v217
	v_mul_f32_e32 v199, v199, v217
	v_fmac_f32_e32 v196, v212, v158
	v_fmac_f32_e32 v197, v212, v159
	v_fmac_f32_e32 v198, v212, v160
	v_fmac_f32_e32 v199, v212, v161
	s_sub_u32 s62, s62, s64
	s_subb_u32 s63, s63, 0
	s_add_u32 s42, s62, 0x1000
	s_addc_u32 s43, s63, 0
	global_load_dwordx4 v[128:131], v214, s[62:63] nt
	global_load_dwordx4 v[146:149], v214, s[62:63] offset:512 nt
	global_load_dwordx4 v[132:135], v214, s[62:63] offset:2048 nt
	global_load_dwordx4 v[150:153], v214, s[62:63] offset:2560 nt
	global_load_dwordx4 v[138:141], v214, s[42:43] nt
	global_load_dwordx4 v[154:157], v214, s[42:43] offset:512 nt
	global_load_dwordx4 v[142:145], v214, s[42:43] offset:2048 nt
	global_load_dwordx4 v[158:161], v214, s[42:43] offset:2560 nt
	s_waitcnt vmcnt(39)
	v_mul_f32_e32 v208, v164, v0
	v_fmac_f32_e32 v208, v165, v1
	v_fmac_f32_e32 v208, v166, v2
	v_fmac_f32_e32 v208, v167, v3
	s_waitcnt vmcnt(37)
	v_mul_f32_e32 v209, v168, v4
	v_fmac_f32_e32 v209, v169, v5
	v_fmac_f32_e32 v209, v170, v6
	v_fmac_f32_e32 v209, v171, v7
	s_waitcnt vmcnt(35)
	v_mul_f32_e32 v210, v172, v8
	v_fmac_f32_e32 v210, v173, v9
	v_fmac_f32_e32 v210, v174, v10
	v_fmac_f32_e32 v210, v175, v11
	s_waitcnt vmcnt(33)
	v_mul_f32_e32 v212, v176, v12
	v_fmac_f32_e32 v212, v177, v13
	v_fmac_f32_e32 v212, v178, v14
	v_fmac_f32_e32 v212, v179, v15
	v_add_f32_dpp v208, v208, v208 quad_perm:[1,0,3,2] row_mask:0xf bank_mask:0xf bound_ctrl:1
	v_add_f32_dpp v209, v209, v209 quad_perm:[1,0,3,2] row_mask:0xf bank_mask:0xf bound_ctrl:1
	v_add_f32_dpp v210, v210, v210 quad_perm:[1,0,3,2] row_mask:0xf bank_mask:0xf bound_ctrl:1
	v_add_f32_dpp v212, v212, v212 quad_perm:[1,0,3,2] row_mask:0xf bank_mask:0xf bound_ctrl:1
	v_add_f32_dpp v208, v208, v208 quad_perm:[2,3,0,1] row_mask:0xf bank_mask:0xf bound_ctrl:1
	v_add_f32_dpp v209, v209, v209 quad_perm:[2,3,0,1] row_mask:0xf bank_mask:0xf bound_ctrl:1
	v_add_f32_dpp v210, v210, v210 quad_perm:[2,3,0,1] row_mask:0xf bank_mask:0xf bound_ctrl:1
	v_add_f32_dpp v212, v212, v212 quad_perm:[2,3,0,1] row_mask:0xf bank_mask:0xf bound_ctrl:1
	v_add_f32_dpp v208, v208, v208 row_ror:4 row_mask:0xf bank_mask:0xf bound_ctrl:1
	v_add_f32_dpp v209, v209, v209 row_ror:4 row_mask:0xf bank_mask:0xf bound_ctrl:1
	v_add_f32_dpp v210, v210, v210 row_ror:4 row_mask:0xf bank_mask:0xf bound_ctrl:1
	v_add_f32_dpp v212, v212, v212 row_ror:4 row_mask:0xf bank_mask:0xf bound_ctrl:1
	v_add_f32_dpp v208, v208, v208 row_ror:8 row_mask:0xf bank_mask:0xf bound_ctrl:1
	v_add_f32_dpp v209, v209, v209 row_ror:8 row_mask:0xf bank_mask:0xf bound_ctrl:1
	v_add_f32_dpp v210, v210, v210 row_ror:8 row_mask:0xf bank_mask:0xf bound_ctrl:1
	v_add_f32_dpp v212, v212, v212 row_ror:8 row_mask:0xf bank_mask:0xf bound_ctrl:1
	v_max_f32_e32 v218, v208, v200
	v_sub_f32_e32 v217, v200, v218
	v_sub_f32_e32 v208, v208, v218
	v_mul_f32_e32 v217, 0x3fb8aa3b, v217
	v_mul_f32_e32 v208, 0x3fb8aa3b, v208
	v_exp_f32_e32 v217, v217
	v_exp_f32_e32 v208, v208
	v_mov_b32_e32 v200, v218
	s_waitcnt vmcnt(38)
	v_fma_f32 v204, v204, v217, v208
	v_mul_f32_e32 v180, v180, v217
	v_mul_f32_e32 v181, v181, v217
	v_mul_f32_e32 v182, v182, v217
	v_mul_f32_e32 v183, v183, v217
	v_fmac_f32_e32 v180, v208, v16
	v_fmac_f32_e32 v181, v208, v17
	v_fmac_f32_e32 v182, v208, v18
	v_fmac_f32_e32 v183, v208, v19
	v_max_f32_e32 v218, v209, v201
	v_sub_f32_e32 v217, v201, v218
	v_sub_f32_e32 v209, v209, v218
	v_mul_f32_e32 v217, 0x3fb8aa3b, v217
	v_mul_f32_e32 v209, 0x3fb8aa3b, v209
	v_exp_f32_e32 v217, v217
	v_exp_f32_e32 v209, v209
	v_mov_b32_e32 v201, v218
	s_waitcnt vmcnt(36)
	v_fma_f32 v205, v205, v217, v209
	v_mul_f32_e32 v184, v184, v217
	v_mul_f32_e32 v185, v185, v217
	v_mul_f32_e32 v186, v186, v217
	v_mul_f32_e32 v187, v187, v217
	v_fmac_f32_e32 v184, v209, v20
	v_fmac_f32_e32 v185, v209, v21
	v_fmac_f32_e32 v186, v209, v22
	v_fmac_f32_e32 v187, v209, v23
	v_max_f32_e32 v218, v210, v202
	v_sub_f32_e32 v217, v202, v218
	v_sub_f32_e32 v210, v210, v218
	v_mul_f32_e32 v217, 0x3fb8aa3b, v217
	v_mul_f32_e32 v210, 0x3fb8aa3b, v210
	v_exp_f32_e32 v217, v217
	v_exp_f32_e32 v210, v210
	v_mov_b32_e32 v202, v218
	s_waitcnt vmcnt(34)
	v_fma_f32 v206, v206, v217, v210
	v_mul_f32_e32 v188, v188, v217
	v_mul_f32_e32 v189, v189, v217
	v_mul_f32_e32 v190, v190, v217
	v_mul_f32_e32 v191, v191, v217
	v_fmac_f32_e32 v188, v210, v24
	v_fmac_f32_e32 v189, v210, v25
	v_fmac_f32_e32 v190, v210, v26
	v_fmac_f32_e32 v191, v210, v27
	v_max_f32_e32 v218, v212, v203
	v_sub_f32_e32 v217, v203, v218
	v_sub_f32_e32 v212, v212, v218
	v_mul_f32_e32 v217, 0x3fb8aa3b, v217
	v_mul_f32_e32 v212, 0x3fb8aa3b, v212
	v_exp_f32_e32 v217, v217
	v_exp_f32_e32 v212, v212
	v_mov_b32_e32 v203, v218
	s_waitcnt vmcnt(32)
	v_fma_f32 v207, v207, v217, v212
	v_mul_f32_e32 v196, v196, v217
	v_mul_f32_e32 v197, v197, v217
	v_mul_f32_e32 v198, v198, v217
	v_mul_f32_e32 v199, v199, v217
	v_fmac_f32_e32 v196, v212, v28
	v_fmac_f32_e32 v197, v212, v29
	v_fmac_f32_e32 v198, v212, v30
	v_fmac_f32_e32 v199, v212, v31
	s_sub_u32 s62, s62, s64
	s_subb_u32 s63, s63, 0
	s_add_u32 s42, s62, 0x1000
	s_addc_u32 s43, s63, 0
	global_load_dwordx4 v[0:3], v214, s[62:63] nt
	global_load_dwordx4 v[16:19], v214, s[62:63] offset:512 nt
	global_load_dwordx4 v[4:7], v214, s[62:63] offset:2048 nt
	global_load_dwordx4 v[20:23], v214, s[62:63] offset:2560 nt
	global_load_dwordx4 v[8:11], v214, s[42:43] nt
	global_load_dwordx4 v[24:27], v214, s[42:43] offset:512 nt
	global_load_dwordx4 v[12:15], v214, s[42:43] offset:2048 nt
	global_load_dwordx4 v[28:31], v214, s[42:43] offset:2560 nt
	s_waitcnt vmcnt(39)
	v_mul_f32_e32 v208, v164, v32
	v_fmac_f32_e32 v208, v165, v33
	v_fmac_f32_e32 v208, v166, v34
	v_fmac_f32_e32 v208, v167, v35
	s_waitcnt vmcnt(37)
	v_mul_f32_e32 v209, v168, v36
	v_fmac_f32_e32 v209, v169, v37
	v_fmac_f32_e32 v209, v170, v38
	v_fmac_f32_e32 v209, v171, v39
	s_waitcnt vmcnt(35)
	v_mul_f32_e32 v210, v172, v40
	v_fmac_f32_e32 v210, v173, v41
	v_fmac_f32_e32 v210, v174, v42
	v_fmac_f32_e32 v210, v175, v43
	s_waitcnt vmcnt(33)
	v_mul_f32_e32 v212, v176, v44
	v_fmac_f32_e32 v212, v177, v45
	v_fmac_f32_e32 v212, v178, v46
	v_fmac_f32_e32 v212, v179, v47
	v_add_f32_dpp v208, v208, v208 quad_perm:[1,0,3,2] row_mask:0xf bank_mask:0xf bound_ctrl:1
	v_add_f32_dpp v209, v209, v209 quad_perm:[1,0,3,2] row_mask:0xf bank_mask:0xf bound_ctrl:1
	v_add_f32_dpp v210, v210, v210 quad_perm:[1,0,3,2] row_mask:0xf bank_mask:0xf bound_ctrl:1
	v_add_f32_dpp v212, v212, v212 quad_perm:[1,0,3,2] row_mask:0xf bank_mask:0xf bound_ctrl:1
	v_add_f32_dpp v208, v208, v208 quad_perm:[2,3,0,1] row_mask:0xf bank_mask:0xf bound_ctrl:1
	v_add_f32_dpp v209, v209, v209 quad_perm:[2,3,0,1] row_mask:0xf bank_mask:0xf bound_ctrl:1
	v_add_f32_dpp v210, v210, v210 quad_perm:[2,3,0,1] row_mask:0xf bank_mask:0xf bound_ctrl:1
	v_add_f32_dpp v212, v212, v212 quad_perm:[2,3,0,1] row_mask:0xf bank_mask:0xf bound_ctrl:1
	v_add_f32_dpp v208, v208, v208 row_ror:4 row_mask:0xf bank_mask:0xf bound_ctrl:1
	v_add_f32_dpp v209, v209, v209 row_ror:4 row_mask:0xf bank_mask:0xf bound_ctrl:1
	v_add_f32_dpp v210, v210, v210 row_ror:4 row_mask:0xf bank_mask:0xf bound_ctrl:1
	v_add_f32_dpp v212, v212, v212 row_ror:4 row_mask:0xf bank_mask:0xf bound_ctrl:1
	v_add_f32_dpp v208, v208, v208 row_ror:8 row_mask:0xf bank_mask:0xf bound_ctrl:1
	v_add_f32_dpp v209, v209, v209 row_ror:8 row_mask:0xf bank_mask:0xf bound_ctrl:1
	v_add_f32_dpp v210, v210, v210 row_ror:8 row_mask:0xf bank_mask:0xf bound_ctrl:1
	v_add_f32_dpp v212, v212, v212 row_ror:8 row_mask:0xf bank_mask:0xf bound_ctrl:1
	v_max_f32_e32 v218, v208, v200
	v_sub_f32_e32 v217, v200, v218
	v_sub_f32_e32 v208, v208, v218
	v_mul_f32_e32 v217, 0x3fb8aa3b, v217
	v_mul_f32_e32 v208, 0x3fb8aa3b, v208
	v_exp_f32_e32 v217, v217
	v_exp_f32_e32 v208, v208
	v_mov_b32_e32 v200, v218
	s_waitcnt vmcnt(38)
	v_fma_f32 v204, v204, v217, v208
	v_mul_f32_e32 v180, v180, v217
	v_mul_f32_e32 v181, v181, v217
	v_mul_f32_e32 v182, v182, v217
	v_mul_f32_e32 v183, v183, v217
	v_fmac_f32_e32 v180, v208, v48
	v_fmac_f32_e32 v181, v208, v49
	v_fmac_f32_e32 v182, v208, v50
	v_fmac_f32_e32 v183, v208, v51
	v_max_f32_e32 v218, v209, v201
	v_sub_f32_e32 v217, v201, v218
	v_sub_f32_e32 v209, v209, v218
	v_mul_f32_e32 v217, 0x3fb8aa3b, v217
	v_mul_f32_e32 v209, 0x3fb8aa3b, v209
	v_exp_f32_e32 v217, v217
	v_exp_f32_e32 v209, v209
	v_mov_b32_e32 v201, v218
	s_waitcnt vmcnt(36)
	v_fma_f32 v205, v205, v217, v209
	v_mul_f32_e32 v184, v184, v217
	v_mul_f32_e32 v185, v185, v217
	v_mul_f32_e32 v186, v186, v217
	v_mul_f32_e32 v187, v187, v217
	v_fmac_f32_e32 v184, v209, v52
	v_fmac_f32_e32 v185, v209, v53
	v_fmac_f32_e32 v186, v209, v54
	v_fmac_f32_e32 v187, v209, v55
	v_max_f32_e32 v218, v210, v202
	v_sub_f32_e32 v217, v202, v218
	v_sub_f32_e32 v210, v210, v218
	v_mul_f32_e32 v217, 0x3fb8aa3b, v217
	v_mul_f32_e32 v210, 0x3fb8aa3b, v210
	v_exp_f32_e32 v217, v217
	v_exp_f32_e32 v210, v210
	v_mov_b32_e32 v202, v218
	s_waitcnt vmcnt(34)
	v_fma_f32 v206, v206, v217, v210
	v_mul_f32_e32 v188, v188, v217
	v_mul_f32_e32 v189, v189, v217
	v_mul_f32_e32 v190, v190, v217
	v_mul_f32_e32 v191, v191, v217
	v_fmac_f32_e32 v188, v210, v56
	v_fmac_f32_e32 v189, v210, v57
	v_fmac_f32_e32 v190, v210, v58
	v_fmac_f32_e32 v191, v210, v59
	v_max_f32_e32 v218, v212, v203
	v_sub_f32_e32 v217, v203, v218
	v_sub_f32_e32 v212, v212, v218
	v_mul_f32_e32 v217, 0x3fb8aa3b, v217
	v_mul_f32_e32 v212, 0x3fb8aa3b, v212
	v_exp_f32_e32 v217, v217
	v_exp_f32_e32 v212, v212
	v_mov_b32_e32 v203, v218
	s_waitcnt vmcnt(32)
	v_fma_f32 v207, v207, v217, v212
	v_mul_f32_e32 v196, v196, v217
	v_mul_f32_e32 v197, v197, v217
	v_mul_f32_e32 v198, v198, v217
	v_mul_f32_e32 v199, v199, v217
	v_fmac_f32_e32 v196, v212, v60
	v_fmac_f32_e32 v197, v212, v61
	v_fmac_f32_e32 v198, v212, v62
	v_fmac_f32_e32 v199, v212, v63
	s_waitcnt vmcnt(31)
	v_mul_f32_e32 v208, v164, v64
	v_fmac_f32_e32 v208, v165, v65
	v_fmac_f32_e32 v208, v166, v66
	v_fmac_f32_e32 v208, v167, v67
	s_waitcnt vmcnt(29)
	v_mul_f32_e32 v209, v168, v68
	v_fmac_f32_e32 v209, v169, v69
	v_fmac_f32_e32 v209, v170, v70
	v_fmac_f32_e32 v209, v171, v71
	s_waitcnt vmcnt(27)
	v_mul_f32_e32 v210, v172, v72
	v_fmac_f32_e32 v210, v173, v73
	v_fmac_f32_e32 v210, v174, v74
	v_fmac_f32_e32 v210, v175, v75
	s_waitcnt vmcnt(25)
	v_mul_f32_e32 v212, v176, v76
	v_fmac_f32_e32 v212, v177, v77
	v_fmac_f32_e32 v212, v178, v78
	v_fmac_f32_e32 v212, v179, v79
	v_add_f32_dpp v208, v208, v208 quad_perm:[1,0,3,2] row_mask:0xf bank_mask:0xf bound_ctrl:1
	v_add_f32_dpp v209, v209, v209 quad_perm:[1,0,3,2] row_mask:0xf bank_mask:0xf bound_ctrl:1
	v_add_f32_dpp v210, v210, v210 quad_perm:[1,0,3,2] row_mask:0xf bank_mask:0xf bound_ctrl:1
	v_add_f32_dpp v212, v212, v212 quad_perm:[1,0,3,2] row_mask:0xf bank_mask:0xf bound_ctrl:1
	v_add_f32_dpp v208, v208, v208 quad_perm:[2,3,0,1] row_mask:0xf bank_mask:0xf bound_ctrl:1
	v_add_f32_dpp v209, v209, v209 quad_perm:[2,3,0,1] row_mask:0xf bank_mask:0xf bound_ctrl:1
	v_add_f32_dpp v210, v210, v210 quad_perm:[2,3,0,1] row_mask:0xf bank_mask:0xf bound_ctrl:1
	v_add_f32_dpp v212, v212, v212 quad_perm:[2,3,0,1] row_mask:0xf bank_mask:0xf bound_ctrl:1
	v_add_f32_dpp v208, v208, v208 row_ror:4 row_mask:0xf bank_mask:0xf bound_ctrl:1
	v_add_f32_dpp v209, v209, v209 row_ror:4 row_mask:0xf bank_mask:0xf bound_ctrl:1
	v_add_f32_dpp v210, v210, v210 row_ror:4 row_mask:0xf bank_mask:0xf bound_ctrl:1
	v_add_f32_dpp v212, v212, v212 row_ror:4 row_mask:0xf bank_mask:0xf bound_ctrl:1
	v_add_f32_dpp v208, v208, v208 row_ror:8 row_mask:0xf bank_mask:0xf bound_ctrl:1
	v_add_f32_dpp v209, v209, v209 row_ror:8 row_mask:0xf bank_mask:0xf bound_ctrl:1
	v_add_f32_dpp v210, v210, v210 row_ror:8 row_mask:0xf bank_mask:0xf bound_ctrl:1
	v_add_f32_dpp v212, v212, v212 row_ror:8 row_mask:0xf bank_mask:0xf bound_ctrl:1
	v_max_f32_e32 v218, v208, v200
	v_sub_f32_e32 v217, v200, v218
	v_sub_f32_e32 v208, v208, v218
	v_mul_f32_e32 v217, 0x3fb8aa3b, v217
	v_mul_f32_e32 v208, 0x3fb8aa3b, v208
	v_exp_f32_e32 v217, v217
	v_exp_f32_e32 v208, v208
	v_mov_b32_e32 v200, v218
	s_waitcnt vmcnt(30)
	v_fma_f32 v204, v204, v217, v208
	v_mul_f32_e32 v180, v180, v217
	v_mul_f32_e32 v181, v181, v217
	v_mul_f32_e32 v182, v182, v217
	v_mul_f32_e32 v183, v183, v217
	v_fmac_f32_e32 v180, v208, v80
	v_fmac_f32_e32 v181, v208, v81
	v_fmac_f32_e32 v182, v208, v82
	v_fmac_f32_e32 v183, v208, v83
	v_max_f32_e32 v218, v209, v201
	v_sub_f32_e32 v217, v201, v218
	v_sub_f32_e32 v209, v209, v218
	v_mul_f32_e32 v217, 0x3fb8aa3b, v217
	v_mul_f32_e32 v209, 0x3fb8aa3b, v209
	v_exp_f32_e32 v217, v217
	v_exp_f32_e32 v209, v209
	v_mov_b32_e32 v201, v218
	s_waitcnt vmcnt(28)
	v_fma_f32 v205, v205, v217, v209
	v_mul_f32_e32 v184, v184, v217
	v_mul_f32_e32 v185, v185, v217
	v_mul_f32_e32 v186, v186, v217
	v_mul_f32_e32 v187, v187, v217
	v_fmac_f32_e32 v184, v209, v84
	v_fmac_f32_e32 v185, v209, v85
	v_fmac_f32_e32 v186, v209, v86
	v_fmac_f32_e32 v187, v209, v87
	v_max_f32_e32 v218, v210, v202
	v_sub_f32_e32 v217, v202, v218
	v_sub_f32_e32 v210, v210, v218
	v_mul_f32_e32 v217, 0x3fb8aa3b, v217
	v_mul_f32_e32 v210, 0x3fb8aa3b, v210
	v_exp_f32_e32 v217, v217
	v_exp_f32_e32 v210, v210
	v_mov_b32_e32 v202, v218
	s_waitcnt vmcnt(26)
	v_fma_f32 v206, v206, v217, v210
	v_mul_f32_e32 v188, v188, v217
	v_mul_f32_e32 v189, v189, v217
	v_mul_f32_e32 v190, v190, v217
	v_mul_f32_e32 v191, v191, v217
	v_fmac_f32_e32 v188, v210, v88
	v_fmac_f32_e32 v189, v210, v89
	v_fmac_f32_e32 v190, v210, v90
	v_fmac_f32_e32 v191, v210, v91
	v_max_f32_e32 v218, v212, v203
	v_sub_f32_e32 v217, v203, v218
	v_sub_f32_e32 v212, v212, v218
	v_mul_f32_e32 v217, 0x3fb8aa3b, v217
	v_mul_f32_e32 v212, 0x3fb8aa3b, v212
	v_exp_f32_e32 v217, v217
	v_exp_f32_e32 v212, v212
	v_mov_b32_e32 v203, v218
	s_waitcnt vmcnt(24)
	v_fma_f32 v207, v207, v217, v212
	v_mul_f32_e32 v196, v196, v217
	v_mul_f32_e32 v197, v197, v217
	v_mul_f32_e32 v198, v198, v217
	v_mul_f32_e32 v199, v199, v217
	v_fmac_f32_e32 v196, v212, v92
	v_fmac_f32_e32 v197, v212, v93
	v_fmac_f32_e32 v198, v212, v94
	v_fmac_f32_e32 v199, v212, v95
	s_waitcnt vmcnt(23)
	v_mul_f32_e32 v208, v164, v96
	v_fmac_f32_e32 v208, v165, v97
	v_fmac_f32_e32 v208, v166, v98
	v_fmac_f32_e32 v208, v167, v99
	s_waitcnt vmcnt(21)
	v_mul_f32_e32 v209, v168, v100
	v_fmac_f32_e32 v209, v169, v101
	v_fmac_f32_e32 v209, v170, v102
	v_fmac_f32_e32 v209, v171, v103
	s_waitcnt vmcnt(19)
	v_mul_f32_e32 v210, v172, v104
	v_fmac_f32_e32 v210, v173, v105
	v_fmac_f32_e32 v210, v174, v106
	v_fmac_f32_e32 v210, v175, v107
	s_waitcnt vmcnt(17)
	v_mul_f32_e32 v212, v176, v108
	v_fmac_f32_e32 v212, v177, v109
	v_fmac_f32_e32 v212, v178, v110
	v_fmac_f32_e32 v212, v179, v111
	v_add_f32_dpp v208, v208, v208 quad_perm:[1,0,3,2] row_mask:0xf bank_mask:0xf bound_ctrl:1
	v_add_f32_dpp v209, v209, v209 quad_perm:[1,0,3,2] row_mask:0xf bank_mask:0xf bound_ctrl:1
	v_add_f32_dpp v210, v210, v210 quad_perm:[1,0,3,2] row_mask:0xf bank_mask:0xf bound_ctrl:1
	v_add_f32_dpp v212, v212, v212 quad_perm:[1,0,3,2] row_mask:0xf bank_mask:0xf bound_ctrl:1
	v_add_f32_dpp v208, v208, v208 quad_perm:[2,3,0,1] row_mask:0xf bank_mask:0xf bound_ctrl:1
	v_add_f32_dpp v209, v209, v209 quad_perm:[2,3,0,1] row_mask:0xf bank_mask:0xf bound_ctrl:1
	v_add_f32_dpp v210, v210, v210 quad_perm:[2,3,0,1] row_mask:0xf bank_mask:0xf bound_ctrl:1
	v_add_f32_dpp v212, v212, v212 quad_perm:[2,3,0,1] row_mask:0xf bank_mask:0xf bound_ctrl:1
	v_add_f32_dpp v208, v208, v208 row_ror:4 row_mask:0xf bank_mask:0xf bound_ctrl:1
	v_add_f32_dpp v209, v209, v209 row_ror:4 row_mask:0xf bank_mask:0xf bound_ctrl:1
	v_add_f32_dpp v210, v210, v210 row_ror:4 row_mask:0xf bank_mask:0xf bound_ctrl:1
	v_add_f32_dpp v212, v212, v212 row_ror:4 row_mask:0xf bank_mask:0xf bound_ctrl:1
	v_add_f32_dpp v208, v208, v208 row_ror:8 row_mask:0xf bank_mask:0xf bound_ctrl:1
	v_add_f32_dpp v209, v209, v209 row_ror:8 row_mask:0xf bank_mask:0xf bound_ctrl:1
	v_add_f32_dpp v210, v210, v210 row_ror:8 row_mask:0xf bank_mask:0xf bound_ctrl:1
	v_add_f32_dpp v212, v212, v212 row_ror:8 row_mask:0xf bank_mask:0xf bound_ctrl:1
	v_max_f32_e32 v218, v208, v200
	v_sub_f32_e32 v217, v200, v218
	v_sub_f32_e32 v208, v208, v218
	v_mul_f32_e32 v217, 0x3fb8aa3b, v217
	v_mul_f32_e32 v208, 0x3fb8aa3b, v208
	v_exp_f32_e32 v217, v217
	v_exp_f32_e32 v208, v208
	v_mov_b32_e32 v200, v218
	s_waitcnt vmcnt(22)
	v_fma_f32 v204, v204, v217, v208
	v_mul_f32_e32 v180, v180, v217
	v_mul_f32_e32 v181, v181, v217
	v_mul_f32_e32 v182, v182, v217
	v_mul_f32_e32 v183, v183, v217
	v_fmac_f32_e32 v180, v208, v112
	v_fmac_f32_e32 v181, v208, v113
	v_fmac_f32_e32 v182, v208, v114
	v_fmac_f32_e32 v183, v208, v115
	v_max_f32_e32 v218, v209, v201
	v_sub_f32_e32 v217, v201, v218
	v_sub_f32_e32 v209, v209, v218
	v_mul_f32_e32 v217, 0x3fb8aa3b, v217
	v_mul_f32_e32 v209, 0x3fb8aa3b, v209
	v_exp_f32_e32 v217, v217
	v_exp_f32_e32 v209, v209
	v_mov_b32_e32 v201, v218
	s_waitcnt vmcnt(20)
	v_fma_f32 v205, v205, v217, v209
	v_mul_f32_e32 v184, v184, v217
	v_mul_f32_e32 v185, v185, v217
	v_mul_f32_e32 v186, v186, v217
	v_mul_f32_e32 v187, v187, v217
	v_fmac_f32_e32 v184, v209, v116
	v_fmac_f32_e32 v185, v209, v117
	v_fmac_f32_e32 v186, v209, v118
	v_fmac_f32_e32 v187, v209, v119
	v_max_f32_e32 v218, v210, v202
	v_sub_f32_e32 v217, v202, v218
	v_sub_f32_e32 v210, v210, v218
	v_mul_f32_e32 v217, 0x3fb8aa3b, v217
	v_mul_f32_e32 v210, 0x3fb8aa3b, v210
	v_exp_f32_e32 v217, v217
	v_exp_f32_e32 v210, v210
	v_mov_b32_e32 v202, v218
	s_waitcnt vmcnt(18)
	v_fma_f32 v206, v206, v217, v210
	v_mul_f32_e32 v188, v188, v217
	v_mul_f32_e32 v189, v189, v217
	v_mul_f32_e32 v190, v190, v217
	v_mul_f32_e32 v191, v191, v217
	v_fmac_f32_e32 v188, v210, v120
	v_fmac_f32_e32 v189, v210, v121
	v_fmac_f32_e32 v190, v210, v122
	v_fmac_f32_e32 v191, v210, v123
	v_max_f32_e32 v218, v212, v203
	v_sub_f32_e32 v217, v203, v218
	v_sub_f32_e32 v212, v212, v218
	v_mul_f32_e32 v217, 0x3fb8aa3b, v217
	v_mul_f32_e32 v212, 0x3fb8aa3b, v212
	v_exp_f32_e32 v217, v217
	v_exp_f32_e32 v212, v212
	v_mov_b32_e32 v203, v218
	s_waitcnt vmcnt(16)
	v_fma_f32 v207, v207, v217, v212
	v_mul_f32_e32 v196, v196, v217
	v_mul_f32_e32 v197, v197, v217
	v_mul_f32_e32 v198, v198, v217
	v_mul_f32_e32 v199, v199, v217
	v_fmac_f32_e32 v196, v212, v124
	v_fmac_f32_e32 v197, v212, v125
	v_fmac_f32_e32 v198, v212, v126
	v_fmac_f32_e32 v199, v212, v127
	s_waitcnt vmcnt(15)
	v_mul_f32_e32 v208, v164, v128
	v_fmac_f32_e32 v208, v165, v129
	v_fmac_f32_e32 v208, v166, v130
	v_fmac_f32_e32 v208, v167, v131
	s_waitcnt vmcnt(13)
	v_mul_f32_e32 v209, v168, v132
	v_fmac_f32_e32 v209, v169, v133
	v_fmac_f32_e32 v209, v170, v134
	v_fmac_f32_e32 v209, v171, v135
	s_waitcnt vmcnt(11)
	v_mul_f32_e32 v210, v172, v138
	v_fmac_f32_e32 v210, v173, v139
	v_fmac_f32_e32 v210, v174, v140
	v_fmac_f32_e32 v210, v175, v141
	s_waitcnt vmcnt(9)
	v_mul_f32_e32 v212, v176, v142
	v_fmac_f32_e32 v212, v177, v143
	v_fmac_f32_e32 v212, v178, v144
	v_fmac_f32_e32 v212, v179, v145
	v_add_f32_dpp v208, v208, v208 quad_perm:[1,0,3,2] row_mask:0xf bank_mask:0xf bound_ctrl:1
	v_add_f32_dpp v209, v209, v209 quad_perm:[1,0,3,2] row_mask:0xf bank_mask:0xf bound_ctrl:1
	v_add_f32_dpp v210, v210, v210 quad_perm:[1,0,3,2] row_mask:0xf bank_mask:0xf bound_ctrl:1
	v_add_f32_dpp v212, v212, v212 quad_perm:[1,0,3,2] row_mask:0xf bank_mask:0xf bound_ctrl:1
	v_add_f32_dpp v208, v208, v208 quad_perm:[2,3,0,1] row_mask:0xf bank_mask:0xf bound_ctrl:1
	v_add_f32_dpp v209, v209, v209 quad_perm:[2,3,0,1] row_mask:0xf bank_mask:0xf bound_ctrl:1
	v_add_f32_dpp v210, v210, v210 quad_perm:[2,3,0,1] row_mask:0xf bank_mask:0xf bound_ctrl:1
	v_add_f32_dpp v212, v212, v212 quad_perm:[2,3,0,1] row_mask:0xf bank_mask:0xf bound_ctrl:1
	v_add_f32_dpp v208, v208, v208 row_ror:4 row_mask:0xf bank_mask:0xf bound_ctrl:1
	v_add_f32_dpp v209, v209, v209 row_ror:4 row_mask:0xf bank_mask:0xf bound_ctrl:1
	v_add_f32_dpp v210, v210, v210 row_ror:4 row_mask:0xf bank_mask:0xf bound_ctrl:1
	v_add_f32_dpp v212, v212, v212 row_ror:4 row_mask:0xf bank_mask:0xf bound_ctrl:1
	v_add_f32_dpp v208, v208, v208 row_ror:8 row_mask:0xf bank_mask:0xf bound_ctrl:1
	v_add_f32_dpp v209, v209, v209 row_ror:8 row_mask:0xf bank_mask:0xf bound_ctrl:1
	v_add_f32_dpp v210, v210, v210 row_ror:8 row_mask:0xf bank_mask:0xf bound_ctrl:1
	v_add_f32_dpp v212, v212, v212 row_ror:8 row_mask:0xf bank_mask:0xf bound_ctrl:1
	v_max_f32_e32 v218, v208, v200
	v_sub_f32_e32 v217, v200, v218
	v_sub_f32_e32 v208, v208, v218
	v_mul_f32_e32 v217, 0x3fb8aa3b, v217
	v_mul_f32_e32 v208, 0x3fb8aa3b, v208
	v_exp_f32_e32 v217, v217
	v_exp_f32_e32 v208, v208
	v_mov_b32_e32 v200, v218
	s_waitcnt vmcnt(14)
	v_fma_f32 v204, v204, v217, v208
	v_mul_f32_e32 v180, v180, v217
	v_mul_f32_e32 v181, v181, v217
	v_mul_f32_e32 v182, v182, v217
	v_mul_f32_e32 v183, v183, v217
	v_fmac_f32_e32 v180, v208, v146
	v_fmac_f32_e32 v181, v208, v147
	v_fmac_f32_e32 v182, v208, v148
	v_fmac_f32_e32 v183, v208, v149
	v_max_f32_e32 v218, v209, v201
	v_sub_f32_e32 v217, v201, v218
	v_sub_f32_e32 v209, v209, v218
	v_mul_f32_e32 v217, 0x3fb8aa3b, v217
	v_mul_f32_e32 v209, 0x3fb8aa3b, v209
	v_exp_f32_e32 v217, v217
	v_exp_f32_e32 v209, v209
	v_mov_b32_e32 v201, v218
	s_waitcnt vmcnt(12)
	v_fma_f32 v205, v205, v217, v209
	v_mul_f32_e32 v184, v184, v217
	v_mul_f32_e32 v185, v185, v217
	v_mul_f32_e32 v186, v186, v217
	v_mul_f32_e32 v187, v187, v217
	v_fmac_f32_e32 v184, v209, v150
	v_fmac_f32_e32 v185, v209, v151
	v_fmac_f32_e32 v186, v209, v152
	v_fmac_f32_e32 v187, v209, v153
	v_max_f32_e32 v218, v210, v202
	v_sub_f32_e32 v217, v202, v218
	v_sub_f32_e32 v210, v210, v218
	v_mul_f32_e32 v217, 0x3fb8aa3b, v217
	v_mul_f32_e32 v210, 0x3fb8aa3b, v210
	v_exp_f32_e32 v217, v217
	v_exp_f32_e32 v210, v210
	v_mov_b32_e32 v202, v218
	s_waitcnt vmcnt(10)
	v_fma_f32 v206, v206, v217, v210
	v_mul_f32_e32 v188, v188, v217
	v_mul_f32_e32 v189, v189, v217
	v_mul_f32_e32 v190, v190, v217
	v_mul_f32_e32 v191, v191, v217
	v_fmac_f32_e32 v188, v210, v154
	v_fmac_f32_e32 v189, v210, v155
	v_fmac_f32_e32 v190, v210, v156
	v_fmac_f32_e32 v191, v210, v157
	v_max_f32_e32 v218, v212, v203
	v_sub_f32_e32 v217, v203, v218
	v_sub_f32_e32 v212, v212, v218
	v_mul_f32_e32 v217, 0x3fb8aa3b, v217
	v_mul_f32_e32 v212, 0x3fb8aa3b, v212
	v_exp_f32_e32 v217, v217
	v_exp_f32_e32 v212, v212
	v_mov_b32_e32 v203, v218
	s_waitcnt vmcnt(8)
	v_fma_f32 v207, v207, v217, v212
	v_mul_f32_e32 v196, v196, v217
	v_mul_f32_e32 v197, v197, v217
	v_mul_f32_e32 v198, v198, v217
	v_mul_f32_e32 v199, v199, v217
	v_fmac_f32_e32 v196, v212, v158
	v_fmac_f32_e32 v197, v212, v159
	v_fmac_f32_e32 v198, v212, v160
	v_fmac_f32_e32 v199, v212, v161
	s_waitcnt vmcnt(7)
	v_mul_f32_e32 v208, v164, v0
	v_fmac_f32_e32 v208, v165, v1
	v_fmac_f32_e32 v208, v166, v2
	v_fmac_f32_e32 v208, v167, v3
	s_waitcnt vmcnt(5)
	v_mul_f32_e32 v209, v168, v4
	v_fmac_f32_e32 v209, v169, v5
	v_fmac_f32_e32 v209, v170, v6
	v_fmac_f32_e32 v209, v171, v7
	s_waitcnt vmcnt(3)
	v_mul_f32_e32 v210, v172, v8
	v_fmac_f32_e32 v210, v173, v9
	v_fmac_f32_e32 v210, v174, v10
	v_fmac_f32_e32 v210, v175, v11
	s_waitcnt vmcnt(1)
	v_mul_f32_e32 v212, v176, v12
	v_fmac_f32_e32 v212, v177, v13
	v_fmac_f32_e32 v212, v178, v14
	v_fmac_f32_e32 v212, v179, v15
	v_add_f32_dpp v208, v208, v208 quad_perm:[1,0,3,2] row_mask:0xf bank_mask:0xf bound_ctrl:1
	v_add_f32_dpp v209, v209, v209 quad_perm:[1,0,3,2] row_mask:0xf bank_mask:0xf bound_ctrl:1
	v_add_f32_dpp v210, v210, v210 quad_perm:[1,0,3,2] row_mask:0xf bank_mask:0xf bound_ctrl:1
	v_add_f32_dpp v212, v212, v212 quad_perm:[1,0,3,2] row_mask:0xf bank_mask:0xf bound_ctrl:1
	v_add_f32_dpp v208, v208, v208 quad_perm:[2,3,0,1] row_mask:0xf bank_mask:0xf bound_ctrl:1
	v_add_f32_dpp v209, v209, v209 quad_perm:[2,3,0,1] row_mask:0xf bank_mask:0xf bound_ctrl:1
	v_add_f32_dpp v210, v210, v210 quad_perm:[2,3,0,1] row_mask:0xf bank_mask:0xf bound_ctrl:1
	v_add_f32_dpp v212, v212, v212 quad_perm:[2,3,0,1] row_mask:0xf bank_mask:0xf bound_ctrl:1
	v_add_f32_dpp v208, v208, v208 row_ror:4 row_mask:0xf bank_mask:0xf bound_ctrl:1
	v_add_f32_dpp v209, v209, v209 row_ror:4 row_mask:0xf bank_mask:0xf bound_ctrl:1
	v_add_f32_dpp v210, v210, v210 row_ror:4 row_mask:0xf bank_mask:0xf bound_ctrl:1
	v_add_f32_dpp v212, v212, v212 row_ror:4 row_mask:0xf bank_mask:0xf bound_ctrl:1
	v_add_f32_dpp v208, v208, v208 row_ror:8 row_mask:0xf bank_mask:0xf bound_ctrl:1
	v_add_f32_dpp v209, v209, v209 row_ror:8 row_mask:0xf bank_mask:0xf bound_ctrl:1
	v_add_f32_dpp v210, v210, v210 row_ror:8 row_mask:0xf bank_mask:0xf bound_ctrl:1
	v_add_f32_dpp v212, v212, v212 row_ror:8 row_mask:0xf bank_mask:0xf bound_ctrl:1
	v_max_f32_e32 v218, v208, v200
	v_sub_f32_e32 v217, v200, v218
	v_sub_f32_e32 v208, v208, v218
	v_mul_f32_e32 v217, 0x3fb8aa3b, v217
	v_mul_f32_e32 v208, 0x3fb8aa3b, v208
	v_exp_f32_e32 v217, v217
	v_exp_f32_e32 v208, v208
	v_mov_b32_e32 v200, v218
	s_waitcnt vmcnt(6)
	v_fma_f32 v204, v204, v217, v208
	v_mul_f32_e32 v180, v180, v217
	v_mul_f32_e32 v181, v181, v217
	v_mul_f32_e32 v182, v182, v217
	v_mul_f32_e32 v183, v183, v217
	v_fmac_f32_e32 v180, v208, v16
	v_fmac_f32_e32 v181, v208, v17
	v_fmac_f32_e32 v182, v208, v18
	v_fmac_f32_e32 v183, v208, v19
	v_max_f32_e32 v218, v209, v201
	v_sub_f32_e32 v217, v201, v218
	v_sub_f32_e32 v209, v209, v218
	v_mul_f32_e32 v217, 0x3fb8aa3b, v217
	v_mul_f32_e32 v209, 0x3fb8aa3b, v209
	v_exp_f32_e32 v217, v217
	v_exp_f32_e32 v209, v209
	v_mov_b32_e32 v201, v218
	s_waitcnt vmcnt(4)
	v_fma_f32 v205, v205, v217, v209
	v_mul_f32_e32 v184, v184, v217
	v_mul_f32_e32 v185, v185, v217
	v_mul_f32_e32 v186, v186, v217
	v_mul_f32_e32 v187, v187, v217
	v_fmac_f32_e32 v184, v209, v20
	v_fmac_f32_e32 v185, v209, v21
	v_fmac_f32_e32 v186, v209, v22
	v_fmac_f32_e32 v187, v209, v23
	v_max_f32_e32 v218, v210, v202
	v_sub_f32_e32 v217, v202, v218
	v_sub_f32_e32 v210, v210, v218
	v_mul_f32_e32 v217, 0x3fb8aa3b, v217
	v_mul_f32_e32 v210, 0x3fb8aa3b, v210
	v_exp_f32_e32 v217, v217
	v_exp_f32_e32 v210, v210
	v_mov_b32_e32 v202, v218
	s_waitcnt vmcnt(2)
	v_fma_f32 v206, v206, v217, v210
	v_mul_f32_e32 v188, v188, v217
	v_mul_f32_e32 v189, v189, v217
	v_mul_f32_e32 v190, v190, v217
	v_mul_f32_e32 v191, v191, v217
	v_fmac_f32_e32 v188, v210, v24
	v_fmac_f32_e32 v189, v210, v25
	v_fmac_f32_e32 v190, v210, v26
	v_fmac_f32_e32 v191, v210, v27
	v_max_f32_e32 v218, v212, v203
	v_sub_f32_e32 v217, v203, v218
	v_sub_f32_e32 v212, v212, v218
	v_mul_f32_e32 v217, 0x3fb8aa3b, v217
	v_mul_f32_e32 v212, 0x3fb8aa3b, v212
	v_exp_f32_e32 v217, v217
	v_exp_f32_e32 v212, v212
	v_mov_b32_e32 v203, v218
	s_waitcnt vmcnt(0)
	v_fma_f32 v207, v207, v217, v212
	v_mul_f32_e32 v196, v196, v217
	v_mul_f32_e32 v197, v197, v217
	v_mul_f32_e32 v198, v198, v217
	v_mul_f32_e32 v199, v199, v217
	v_fmac_f32_e32 v196, v212, v28
	v_fmac_f32_e32 v197, v212, v29
	v_fmac_f32_e32 v198, v212, v30
	v_fmac_f32_e32 v199, v212, v31
	s_cmp_lg_u32 s4, 0
	s_cbranch_scc1 .Lst5_noextra
	s_waitcnt vmcnt(0)
	s_sub_u32 s62, s62, s64
	s_subb_u32 s63, s63, 0
	s_add_u32 s42, s62, 0x1000
	s_addc_u32 s43, s63, 0
	global_load_dwordx4 v[32:35], v214, s[62:63] nt
	global_load_dwordx4 v[48:51], v214, s[62:63] offset:512 nt
	global_load_dwordx4 v[36:39], v214, s[62:63] offset:2048 nt
	global_load_dwordx4 v[52:55], v214, s[62:63] offset:2560 nt
	global_load_dwordx4 v[40:43], v214, s[42:43] nt
	global_load_dwordx4 v[56:59], v214, s[42:43] offset:512 nt
	global_load_dwordx4 v[44:47], v214, s[42:43] offset:2048 nt
	global_load_dwordx4 v[60:63], v214, s[42:43] offset:2560 nt
	s_waitcnt vmcnt(7)
	v_mul_f32_e32 v208, v164, v32
	v_fmac_f32_e32 v208, v165, v33
	v_fmac_f32_e32 v208, v166, v34
	v_fmac_f32_e32 v208, v167, v35
	s_waitcnt vmcnt(5)
	v_mul_f32_e32 v209, v168, v36
	v_fmac_f32_e32 v209, v169, v37
	v_fmac_f32_e32 v209, v170, v38
	v_fmac_f32_e32 v209, v171, v39
	s_waitcnt vmcnt(3)
	v_mul_f32_e32 v210, v172, v40
	v_fmac_f32_e32 v210, v173, v41
	v_fmac_f32_e32 v210, v174, v42
	v_fmac_f32_e32 v210, v175, v43
	s_waitcnt vmcnt(1)
	v_mul_f32_e32 v212, v176, v44
	v_fmac_f32_e32 v212, v177, v45
	v_fmac_f32_e32 v212, v178, v46
	v_fmac_f32_e32 v212, v179, v47
	v_add_f32_dpp v208, v208, v208 quad_perm:[1,0,3,2] row_mask:0xf bank_mask:0xf bound_ctrl:1
	v_add_f32_dpp v209, v209, v209 quad_perm:[1,0,3,2] row_mask:0xf bank_mask:0xf bound_ctrl:1
	v_add_f32_dpp v210, v210, v210 quad_perm:[1,0,3,2] row_mask:0xf bank_mask:0xf bound_ctrl:1
	v_add_f32_dpp v212, v212, v212 quad_perm:[1,0,3,2] row_mask:0xf bank_mask:0xf bound_ctrl:1
	v_add_f32_dpp v208, v208, v208 quad_perm:[2,3,0,1] row_mask:0xf bank_mask:0xf bound_ctrl:1
	v_add_f32_dpp v209, v209, v209 quad_perm:[2,3,0,1] row_mask:0xf bank_mask:0xf bound_ctrl:1
	v_add_f32_dpp v210, v210, v210 quad_perm:[2,3,0,1] row_mask:0xf bank_mask:0xf bound_ctrl:1
	v_add_f32_dpp v212, v212, v212 quad_perm:[2,3,0,1] row_mask:0xf bank_mask:0xf bound_ctrl:1
	v_add_f32_dpp v208, v208, v208 row_ror:4 row_mask:0xf bank_mask:0xf bound_ctrl:1
	v_add_f32_dpp v209, v209, v209 row_ror:4 row_mask:0xf bank_mask:0xf bound_ctrl:1
	v_add_f32_dpp v210, v210, v210 row_ror:4 row_mask:0xf bank_mask:0xf bound_ctrl:1
	v_add_f32_dpp v212, v212, v212 row_ror:4 row_mask:0xf bank_mask:0xf bound_ctrl:1
	v_add_f32_dpp v208, v208, v208 row_ror:8 row_mask:0xf bank_mask:0xf bound_ctrl:1
	v_add_f32_dpp v209, v209, v209 row_ror:8 row_mask:0xf bank_mask:0xf bound_ctrl:1
	v_add_f32_dpp v210, v210, v210 row_ror:8 row_mask:0xf bank_mask:0xf bound_ctrl:1
	v_add_f32_dpp v212, v212, v212 row_ror:8 row_mask:0xf bank_mask:0xf bound_ctrl:1
	v_max_f32_e32 v218, v208, v200
	v_sub_f32_e32 v217, v200, v218
	v_sub_f32_e32 v208, v208, v218
	v_mul_f32_e32 v217, 0x3fb8aa3b, v217
	v_mul_f32_e32 v208, 0x3fb8aa3b, v208
	v_exp_f32_e32 v217, v217
	v_exp_f32_e32 v208, v208
	v_mov_b32_e32 v200, v218
	s_waitcnt vmcnt(6)
	v_fma_f32 v204, v204, v217, v208
	v_mul_f32_e32 v180, v180, v217
	v_mul_f32_e32 v181, v181, v217
	v_mul_f32_e32 v182, v182, v217
	v_mul_f32_e32 v183, v183, v217
	v_fmac_f32_e32 v180, v208, v48
	v_fmac_f32_e32 v181, v208, v49
	v_fmac_f32_e32 v182, v208, v50
	v_fmac_f32_e32 v183, v208, v51
	v_max_f32_e32 v218, v209, v201
	v_sub_f32_e32 v217, v201, v218
	v_sub_f32_e32 v209, v209, v218
	v_mul_f32_e32 v217, 0x3fb8aa3b, v217
	v_mul_f32_e32 v209, 0x3fb8aa3b, v209
	v_exp_f32_e32 v217, v217
	v_exp_f32_e32 v209, v209
	v_mov_b32_e32 v201, v218
	s_waitcnt vmcnt(4)
	v_fma_f32 v205, v205, v217, v209
	v_mul_f32_e32 v184, v184, v217
	v_mul_f32_e32 v185, v185, v217
	v_mul_f32_e32 v186, v186, v217
	v_mul_f32_e32 v187, v187, v217
	v_fmac_f32_e32 v184, v209, v52
	v_fmac_f32_e32 v185, v209, v53
	v_fmac_f32_e32 v186, v209, v54
	v_fmac_f32_e32 v187, v209, v55
	v_max_f32_e32 v218, v210, v202
	v_sub_f32_e32 v217, v202, v218
	v_sub_f32_e32 v210, v210, v218
	v_mul_f32_e32 v217, 0x3fb8aa3b, v217
	v_mul_f32_e32 v210, 0x3fb8aa3b, v210
	v_exp_f32_e32 v217, v217
	v_exp_f32_e32 v210, v210
	v_mov_b32_e32 v202, v218
	s_waitcnt vmcnt(2)
	v_fma_f32 v206, v206, v217, v210
	v_mul_f32_e32 v188, v188, v217
	v_mul_f32_e32 v189, v189, v217
	v_mul_f32_e32 v190, v190, v217
	v_mul_f32_e32 v191, v191, v217
	v_fmac_f32_e32 v188, v210, v56
	v_fmac_f32_e32 v189, v210, v57
	v_fmac_f32_e32 v190, v210, v58
	v_fmac_f32_e32 v191, v210, v59
	v_max_f32_e32 v218, v212, v203
	v_sub_f32_e32 v217, v203, v218
	v_sub_f32_e32 v212, v212, v218
	v_mul_f32_e32 v217, 0x3fb8aa3b, v217
	v_mul_f32_e32 v212, 0x3fb8aa3b, v212
	v_exp_f32_e32 v217, v217
	v_exp_f32_e32 v212, v212
	v_mov_b32_e32 v203, v218
	s_waitcnt vmcnt(0)
	v_fma_f32 v207, v207, v217, v212
	v_mul_f32_e32 v196, v196, v217
	v_mul_f32_e32 v197, v197, v217
	v_mul_f32_e32 v198, v198, v217
	v_mul_f32_e32 v199, v199, v217
	v_fmac_f32_e32 v196, v212, v60
	v_fmac_f32_e32 v197, v212, v61
	v_fmac_f32_e32 v198, v212, v62
	v_fmac_f32_e32 v199, v212, v63
.Lst5_noextra:
	s_waitcnt vmcnt(0) lgkmcnt(0)
	s_barrier
	v_and_b32_e32 v218, 63, v192
	v_and_b32_e32 v219, 31, v218
	v_lshrrev_b32_e32 v220, 5, v218
	v_lshlrev_b32_e32 v221, 4, v219
	v_lshl_add_u32 v221, v220, 12, v221
	s_lshl_b32 s28, s4, 9
	s_add_u32 s28, s28, 16
	v_add_u32_e32 v221, s28, v221
	v_lshrrev_b32_e32 v219, 4, v219
	v_lshlrev_b32_e32 v219, 3, v219
	v_lshl_add_u32 v219, v220, 7, v219
	s_lshl_b32 s28, s4, 4
	s_add_u32 s28, s28, 0x8010
	v_add_u32_e32 v219, s28, v219
	ds_write_b128 v221, v[180:183] offset:0
	ds_write_b128 v221, v[184:187] offset:8192
	ds_write_b128 v221, v[188:191] offset:16384
	ds_write_b128 v221, v[196:199] offset:24576
	s_mov_b64 s[40:41], exec
	s_mov_b32 exec_lo, 0x10001
	s_mov_b32 exec_hi, 0x10001
	v_mov_b32_e32 v222, v200
	v_mov_b32_e32 v223, v204
	ds_write_b64 v219, v[222:223] offset:0
	v_mov_b32_e32 v222, v201
	v_mov_b32_e32 v223, v205
	ds_write_b64 v219, v[222:223] offset:256
	v_mov_b32_e32 v222, v202
	v_mov_b32_e32 v223, v206
	ds_write_b64 v219, v[222:223] offset:512
	v_mov_b32_e32 v222, v203
	v_mov_b32_e32 v223, v207
	ds_write_b64 v219, v[222:223] offset:768
	s_mov_b64 exec, s[40:41]
	s_waitcnt lgkmcnt(0)
	s_barrier
	s_mov_b32 exec_hi, 0
	v_and_b32_e32 v219, 31, v192
	v_lshlrev_b32_e32 v221, 4, v219
	s_lshl_b32 s28, s4, 12
	s_add_u32 s28, s28, 16
	v_add_u32_e32 v221, s28, v221
	v_lshrrev_b32_e32 v220, 4, v219
	v_lshlrev_b32_e32 v220, 3, v220
	s_lshl_b32 s28, s4, 7
	s_add_u32 s28, s28, 0x8010
	v_add_u32_e32 v220, s28, v220
	ds_read_b64 v[0:1], v220 offset:0
	ds_read_b64 v[2:3], v220 offset:16
	ds_read_b64 v[4:5], v220 offset:32
	ds_read_b64 v[6:7], v220 offset:48
	ds_read_b64 v[8:9], v220 offset:64
	ds_read_b64 v[10:11], v220 offset:80
	ds_read_b64 v[12:13], v220 offset:96
	ds_read_b64 v[14:15], v220 offset:112
	ds_read_b128 v[16:19], v221 offset:0
	ds_read_b128 v[20:23], v221 offset:512
	ds_read_b128 v[24:27], v221 offset:1024
	ds_read_b128 v[28:31], v221 offset:1536
	ds_read_b128 v[32:35], v221 offset:2048
	ds_read_b128 v[36:39], v221 offset:2560
	ds_read_b128 v[40:43], v221 offset:3072
	ds_read_b128 v[44:47], v221 offset:3584
	s_waitcnt lgkmcnt(0)
	v_max3_f32 v218, v0, v2, v4
	v_max3_f32 v218, v218, v6, v8
	v_max3_f32 v218, v218, v10, v12
	v_max_f32_e32 v218, v218, v14
	v_sub_f32_e32 v0, v0, v218
	v_sub_f32_e32 v2, v2, v218
	v_sub_f32_e32 v4, v4, v218
	v_sub_f32_e32 v6, v6, v218
	v_sub_f32_e32 v8, v8, v218
	v_sub_f32_e32 v10, v10, v218
	v_sub_f32_e32 v12, v12, v218
	v_sub_f32_e32 v14, v14, v218
	v_mul_f32_e32 v0, 0x3fb8aa3b, v0
	v_mul_f32_e32 v2, 0x3fb8aa3b, v2
	v_mul_f32_e32 v4, 0x3fb8aa3b, v4
	v_mul_f32_e32 v6, 0x3fb8aa3b, v6
	v_mul_f32_e32 v8, 0x3fb8aa3b, v8
	v_mul_f32_e32 v10, 0x3fb8aa3b, v10
	v_mul_f32_e32 v12, 0x3fb8aa3b, v12
	v_mul_f32_e32 v14, 0x3fb8aa3b, v14
	v_exp_f32_e32 v0, v0
	v_exp_f32_e32 v2, v2
	v_exp_f32_e32 v4, v4
	v_exp_f32_e32 v6, v6
	v_exp_f32_e32 v8, v8
	v_exp_f32_e32 v10, v10
	v_exp_f32_e32 v12, v12
	v_exp_f32_e32 v14, v14
	s_nop 0
	v_mul_f32_e32 v217, v1, v0
	v_fmac_f32_e32 v217, v3, v2
	v_fmac_f32_e32 v217, v5, v4
	v_fmac_f32_e32 v217, v7, v6
	v_fmac_f32_e32 v217, v9, v8
	v_fmac_f32_e32 v217, v11, v10
	v_fmac_f32_e32 v217, v13, v12
	v_fmac_f32_e32 v217, v15, v14
	v_mul_f32_e32 v48, v16, v0
	v_mul_f32_e32 v49, v17, v0
	v_mul_f32_e32 v50, v18, v0
	v_mul_f32_e32 v51, v19, v0
	v_fmac_f32_e32 v48, v20, v2
	v_fmac_f32_e32 v49, v21, v2
	v_fmac_f32_e32 v50, v22, v2
	v_fmac_f32_e32 v51, v23, v2
	v_fmac_f32_e32 v48, v24, v4
	v_fmac_f32_e32 v49, v25, v4
	v_fmac_f32_e32 v50, v26, v4
	v_fmac_f32_e32 v51, v27, v4
	v_fmac_f32_e32 v48, v28, v6
	v_fmac_f32_e32 v49, v29, v6
	v_fmac_f32_e32 v50, v30, v6
	v_fmac_f32_e32 v51, v31, v6
	v_fmac_f32_e32 v48, v32, v8
	v_fmac_f32_e32 v49, v33, v8
	v_fmac_f32_e32 v50, v34, v8
	v_fmac_f32_e32 v51, v35, v8
	v_fmac_f32_e32 v48, v36, v10
	v_fmac_f32_e32 v49, v37, v10
	v_fmac_f32_e32 v50, v38, v10
	v_fmac_f32_e32 v51, v39, v10
	v_fmac_f32_e32 v48, v40, v12
	v_fmac_f32_e32 v49, v41, v12
	v_fmac_f32_e32 v50, v42, v12
	v_fmac_f32_e32 v51, v43, v12
	v_fmac_f32_e32 v48, v44, v14
	v_fmac_f32_e32 v49, v45, v14
	v_fmac_f32_e32 v50, v46, v14
	v_fmac_f32_e32 v51, v47, v14
	v_rcp_f32_e32 v52, v217
	s_nop 0
	v_fma_f32 v53, -v217, v52, 2.0
	v_mul_f32_e32 v52, v52, v53
	v_mul_f32_e32 v48, v48, v52
	v_mul_f32_e32 v49, v49, v52
	v_mul_f32_e32 v50, v50, v52
	v_mul_f32_e32 v51, v51, v52
	v_cvt_pk_bf16_f32 v54, v48, v49
	v_cvt_pk_bf16_f32 v55, v50, v51
	v_lshlrev_b32_e32 v221, 3, v219
	v_log_f32_e32 v52, v217
	v_lshrrev_b32_e32 v220, 2, v219
	v_mul_f32_e32 v52, 0x3f317218, v52
	v_add_f32_e32 v52, v52, v218
	global_store_dwordx2 v221, v[54:55], s[14:15]
	s_mov_b32 exec_lo, 0x10001
	s_nop 0
	global_store_dword v220, v52, s[22:23]
	s_mov_b64 exec, s[40:41]
